# O4 + MoE SwiGLU epilogue peephole (power-of-two rescalings folded: 2 VALU fewer per gate/up pair, bit-identical)
# speedup vs baseline: 1.0042x; 1.0042x over previous
.LBB0_2878:
	ds_read2_b32 v[2:3], v178 offset1:16
	s_add_u32 s0, s3, s30
	s_addc_u32 s1, s38, s31
	s_add_u32 s0, s0, 0x1b3c3200
	ds_read2_b32 v[168:169], v178 offset0:32 offset1:48
	s_waitcnt lgkmcnt(0)
	v_lshl_add_u32 v161, v2, 10, v1
	v_lshl_add_u32 v163, v3, 10, v176
	ds_read_b128 v[2:5], v179
	ds_read_b128 v[6:9], v184
	ds_read_b128 v[10:13], v185
	ds_read_b128 v[14:17], v186
	s_addc_u32 s1, s1, 0
	s_add_u32 s2, s76, s30
	s_addc_u32 s4, s77, s31
	s_cmpk_eq_i32 s30, 0x300
	s_cselect_b64 vcc, -1, 0
	s_and_b64 s[34:35], vcc, exec
	v_lshl_add_u32 v198, v168, 10, v1
	v_lshl_add_u32 v199, v169, 10, v176
	v_cndmask_b32_e32 v150, v200, v161, vcc
	s_cselect_b32 s37, s17, s1
	s_cselect_b32 s36, s16, s0
	v_cndmask_b32_e32 v172, v158, v163, vcc
	v_cndmask_b32_e32 v201, v160, v198, vcc
	s_cselect_b32 s35, s25, s4
	s_cselect_b32 s34, s75, s2
	v_cndmask_b32_e32 v219, v162, v199, vcc
	v_lshl_add_u64 v[168:169], v[166:167], 0, s[30:31]
	s_add_i32 m0, s42, 0xc000
	ds_read_b128 v[202:205], v196
	ds_read_b128 v[206:209], v196 offset:1024
	ds_read_b128 v[210:213], v196 offset:2048
	ds_read_b128 v[214:217], v196 offset:3072
	ds_read_b128 v[220:223], v196 offset:4096
	ds_read_b128 v[224:227], v196 offset:5120
	ds_read_b128 v[228:231], v196 offset:6144
	ds_read_b128 v[232:235], v196 offset:7168
	global_load_lds_dwordx4 v[168:169], off
	v_lshl_add_u64 v[168:169], v[164:165], 0, s[30:31]
	s_add_i32 m0, s42, 0xe000
	s_nop 0
	global_load_lds_dwordx4 v[168:169], off
	s_waitcnt lgkmcnt(8)
	s_barrier
	s_waitcnt lgkmcnt(0)
	s_setprio 1
	s_waitcnt lgkmcnt(0)
	v_mfma_f32_16x16x128_f8f6f4 v[142:145], v[2:9], v[202:209], v[142:145]
	v_mfma_f32_16x16x128_f8f6f4 v[138:141], v[10:17], v[202:209], v[138:141]
	v_mfma_f32_16x16x128_f8f6f4 v[126:129], v[2:9], v[210:217], v[126:129]
	v_mfma_f32_16x16x128_f8f6f4 v[122:125], v[10:17], v[210:217], v[122:125]
	v_mfma_f32_16x16x128_f8f6f4 v[110:113], v[2:9], v[220:227], v[110:113]
	v_mfma_f32_16x16x128_f8f6f4 v[106:109], v[10:17], v[220:227], v[106:109]
	v_mfma_f32_16x16x128_f8f6f4 v[94:97], v[2:9], v[228:235], v[94:97]
	v_mfma_f32_16x16x128_f8f6f4 v[90:93], v[10:17], v[228:235], v[90:93]
	s_setprio 0
	s_barrier
	s_mov_b32 m0, s43
	v_lshl_add_u64 v[168:169], s[34:35], 0, v[148:149]
	ds_read_b128 v[236:239], v180
	ds_read_b128 v[240:243], v187
	ds_read_b128 v[244:247], v188
	ds_read_b128 v[248:251], v189
	global_load_lds_dwordx4 v[168:169], off
	v_lshl_add_u64 v[170:171], s[34:35], 0, v[146:147]
	s_mov_b32 m0, s44
	s_nop 0
	global_load_lds_dwordx4 v[170:171], off
	s_barrier
	s_waitcnt lgkmcnt(0)
	s_setprio 1
	s_waitcnt lgkmcnt(0)
	v_mfma_f32_16x16x128_f8f6f4 v[134:137], v[236:243], v[202:209], v[134:137]
	v_mfma_f32_16x16x128_f8f6f4 v[130:133], v[244:251], v[202:209], v[130:133]
	v_mfma_f32_16x16x128_f8f6f4 v[118:121], v[236:243], v[210:217], v[118:121]
	v_mfma_f32_16x16x128_f8f6f4 v[114:117], v[244:251], v[210:217], v[114:117]
	v_mfma_f32_16x16x128_f8f6f4 v[102:105], v[236:243], v[220:227], v[102:105]
	v_mfma_f32_16x16x128_f8f6f4 v[98:101], v[244:251], v[220:227], v[98:101]
	v_mfma_f32_16x16x128_f8f6f4 v[86:89], v[236:243], v[228:235], v[86:89]
	v_mfma_f32_16x16x128_f8f6f4 v[82:85], v[244:251], v[228:235], v[82:85]
	s_setprio 0
	s_mov_b32 m0, s42
	s_barrier
	ds_read_b128 v[202:205], v196 offset:16384
	ds_read_b128 v[206:209], v196 offset:17408
	ds_read_b128 v[210:213], v196 offset:18432
	ds_read_b128 v[214:217], v196 offset:19456
	ds_read_b128 v[220:223], v196 offset:20480
	ds_read_b128 v[224:227], v196 offset:21504
	ds_read_b128 v[228:231], v196 offset:22528
	ds_read_b128 v[232:235], v196 offset:23552
	global_load_lds_dwordx4 v150, s[36:37]
	s_mov_b32 m0, s45
	v_mov_b32_e32 v173, v151
	global_load_lds_dwordx4 v172, s[36:37]
	s_barrier
	s_waitcnt lgkmcnt(0)
	v_lshl_add_u64 v[174:175], s[36:37], 0, v[150:151]
	v_lshl_add_u64 v[172:173], s[36:37], 0, v[172:173]
	s_setprio 1
	s_waitcnt lgkmcnt(0)
	v_mfma_f32_16x16x128_f8f6f4 v[78:81], v[2:9], v[202:209], v[78:81]
	v_mfma_f32_16x16x128_f8f6f4 v[74:77], v[10:17], v[202:209], v[74:77]
	v_mfma_f32_16x16x128_f8f6f4 v[62:65], v[2:9], v[210:217], v[62:65]
	v_mfma_f32_16x16x128_f8f6f4 v[58:61], v[10:17], v[210:217], v[58:61]
	v_mfma_f32_16x16x128_f8f6f4 v[46:49], v[2:9], v[220:227], v[46:49]
	v_mfma_f32_16x16x128_f8f6f4 v[42:45], v[10:17], v[220:227], v[42:45]
	v_mfma_f32_16x16x128_f8f6f4 v[30:33], v[2:9], v[228:235], v[30:33]
	v_mfma_f32_16x16x128_f8f6f4 v[26:29], v[10:17], v[228:235], v[26:29]
	s_setprio 0
	s_barrier
	s_add_u32 s66, s34, 0x20000
	s_addc_u32 s67, s35, 0
	s_mov_b32 m0, s46
	v_lshl_add_u64 v[2:3], s[66:67], 0, v[148:149]
	global_load_lds_dwordx4 v[2:3], off
	v_lshl_add_u64 v[2:3], s[66:67], 0, v[146:147]
	s_mov_b32 m0, s47
	s_nop 0
	global_load_lds_dwordx4 v[2:3], off
	s_waitcnt vmcnt(6)
	s_barrier
	s_setprio 1
	v_mfma_f32_16x16x128_f8f6f4 v[70:73], v[236:243], v[202:209], v[70:73]
	v_mfma_f32_16x16x128_f8f6f4 v[66:69], v[244:251], v[202:209], v[66:69]
	v_mfma_f32_16x16x128_f8f6f4 v[54:57], v[236:243], v[210:217], v[54:57]
	v_mfma_f32_16x16x128_f8f6f4 v[50:53], v[244:251], v[210:217], v[50:53]
	v_mfma_f32_16x16x128_f8f6f4 v[38:41], v[236:243], v[220:227], v[38:41]
	v_mfma_f32_16x16x128_f8f6f4 v[34:37], v[244:251], v[220:227], v[34:37]
	v_mfma_f32_16x16x128_f8f6f4 v[22:25], v[236:243], v[228:235], v[22:25]
	v_mfma_f32_16x16x128_f8f6f4 v[18:21], v[244:251], v[228:235], v[18:21]
	s_setprio 0
	s_barrier
	ds_read_b128 v[2:5], v181
	ds_read_b128 v[6:9], v190
	ds_read_b128 v[10:13], v191
	ds_read_b128 v[14:17], v192
	s_mov_b32 m0, s48
	ds_read_b128 v[202:205], v196 offset:32768
	ds_read_b128 v[206:209], v196 offset:33792
	ds_read_b128 v[210:213], v196 offset:34816
	ds_read_b128 v[214:217], v196 offset:35840
	ds_read_b128 v[220:223], v196 offset:36864
	ds_read_b128 v[224:227], v196 offset:37888
	ds_read_b128 v[228:231], v196 offset:38912
	ds_read_b128 v[232:235], v196 offset:39936
	global_load_lds_dwordx4 v201, s[36:37]
	s_mov_b32 m0, s49
	s_nop 0
	global_load_lds_dwordx4 v219, s[36:37]
	s_waitcnt lgkmcnt(8)
	s_barrier
	s_waitcnt lgkmcnt(0)
	s_setprio 1
	s_waitcnt lgkmcnt(0)
	v_mfma_f32_16x16x128_f8f6f4 v[142:145], v[2:9], v[202:209], v[142:145]
	v_mfma_f32_16x16x128_f8f6f4 v[138:141], v[10:17], v[202:209], v[138:141]
	v_mfma_f32_16x16x128_f8f6f4 v[126:129], v[2:9], v[210:217], v[126:129]
	v_mfma_f32_16x16x128_f8f6f4 v[122:125], v[10:17], v[210:217], v[122:125]
	v_mfma_f32_16x16x128_f8f6f4 v[110:113], v[2:9], v[220:227], v[110:113]
	v_mfma_f32_16x16x128_f8f6f4 v[106:109], v[10:17], v[220:227], v[106:109]
	v_mfma_f32_16x16x128_f8f6f4 v[94:97], v[2:9], v[228:235], v[94:97]
	v_mfma_f32_16x16x128_f8f6f4 v[90:93], v[10:17], v[228:235], v[90:93]
	s_setprio 0
	s_barrier
	s_mov_b32 m0, s53
	v_lshl_add_u64 v[168:169], v[168:169], 0, s[20:21]
	ds_read_b128 v[236:239], v182
	ds_read_b128 v[240:243], v193
	ds_read_b128 v[244:247], v194
	ds_read_b128 v[248:251], v195
	global_load_lds_dwordx4 v[168:169], off
	v_lshl_add_u64 v[168:169], v[170:171], 0, s[20:21]
	s_mov_b32 m0, s55
	s_nop 0
	global_load_lds_dwordx4 v[168:169], off
	s_barrier
	s_waitcnt lgkmcnt(0)
	s_setprio 1
	s_waitcnt lgkmcnt(0)
	v_mfma_f32_16x16x128_f8f6f4 v[134:137], v[236:243], v[202:209], v[134:137]
	v_mfma_f32_16x16x128_f8f6f4 v[130:133], v[244:251], v[202:209], v[130:133]
	v_mfma_f32_16x16x128_f8f6f4 v[118:121], v[236:243], v[210:217], v[118:121]
	v_mfma_f32_16x16x128_f8f6f4 v[114:117], v[244:251], v[210:217], v[114:117]
	v_mfma_f32_16x16x128_f8f6f4 v[102:105], v[236:243], v[220:227], v[102:105]
	v_mfma_f32_16x16x128_f8f6f4 v[98:101], v[244:251], v[220:227], v[98:101]
	v_mfma_f32_16x16x128_f8f6f4 v[86:89], v[236:243], v[228:235], v[86:89]
	v_mfma_f32_16x16x128_f8f6f4 v[82:85], v[244:251], v[228:235], v[82:85]
	s_setprio 0
	s_mov_b32 m0, s64
	v_lshl_add_u64 v[168:169], v[174:175], 0, s[20:21]
	s_barrier
	ds_read_b128 v[202:205], v196 offset:49152
	ds_read_b128 v[206:209], v196 offset:50176
	ds_read_b128 v[210:213], v196 offset:51200
	ds_read_b128 v[214:217], v196 offset:52224
	ds_read_b128 v[220:223], v196 offset:53248
	ds_read_b128 v[224:227], v196 offset:54272
	ds_read_b128 v[228:231], v196 offset:55296
	ds_read_b128 v[232:235], v196 offset:56320
	global_load_lds_dwordx4 v[168:169], off
	v_lshl_add_u64 v[168:169], v[172:173], 0, s[20:21]
	s_mov_b32 m0, s65
	s_nop 0
	global_load_lds_dwordx4 v[168:169], off
	s_barrier
	s_waitcnt lgkmcnt(0)
	s_setprio 1
	s_waitcnt lgkmcnt(0)
	v_mfma_f32_16x16x128_f8f6f4 v[78:81], v[2:9], v[202:209], v[78:81]
	v_mfma_f32_16x16x128_f8f6f4 v[74:77], v[10:17], v[202:209], v[74:77]
	v_mfma_f32_16x16x128_f8f6f4 v[62:65], v[2:9], v[210:217], v[62:65]
	v_mfma_f32_16x16x128_f8f6f4 v[58:61], v[10:17], v[210:217], v[58:61]
	v_mfma_f32_16x16x128_f8f6f4 v[46:49], v[2:9], v[220:227], v[46:49]
	v_mfma_f32_16x16x128_f8f6f4 v[42:45], v[10:17], v[220:227], v[42:45]
	v_mfma_f32_16x16x128_f8f6f4 v[30:33], v[2:9], v[228:235], v[30:33]
	v_mfma_f32_16x16x128_f8f6f4 v[26:29], v[10:17], v[228:235], v[26:29]
	s_setprio 0
	s_barrier
	s_add_u32 s34, s34, 0x20080
	s_addc_u32 s35, s35, 0
	s_mov_b32 m0, s68
	v_lshl_add_u64 v[2:3], s[34:35], 0, v[148:149]
	global_load_lds_dwordx4 v[2:3], off
	v_lshl_add_u64 v[2:3], s[34:35], 0, v[146:147]
	s_mov_b32 m0, s69
	s_nop 0
	global_load_lds_dwordx4 v[2:3], off
	s_waitcnt vmcnt(6)
	s_barrier
	s_setprio 1
	v_mfma_f32_16x16x128_f8f6f4 v[70:73], v[236:243], v[202:209], v[70:73]
	v_mfma_f32_16x16x128_f8f6f4 v[66:69], v[244:251], v[202:209], v[66:69]
	v_mfma_f32_16x16x128_f8f6f4 v[54:57], v[236:243], v[210:217], v[54:57]
	v_mfma_f32_16x16x128_f8f6f4 v[50:53], v[244:251], v[210:217], v[50:53]
	v_mfma_f32_16x16x128_f8f6f4 v[38:41], v[236:243], v[220:227], v[38:41]
	v_mfma_f32_16x16x128_f8f6f4 v[34:37], v[244:251], v[220:227], v[34:37]
	v_mfma_f32_16x16x128_f8f6f4 v[22:25], v[236:243], v[228:235], v[22:25]
	v_mfma_f32_16x16x128_f8f6f4 v[18:21], v[244:251], v[228:235], v[18:21]
	s_setprio 0
	s_add_i32 s78, s78, 2
	s_add_u32 s30, s30, 0x100
	s_addc_u32 s31, s31, 0
	s_cmp_gt_u32 s78, 5
	s_barrier
	s_cbranch_scc0 .LBB0_2878
	v_mul_f32_e32 v2, 0xbd38aa3b, v142
	v_exp_f32_e32 v4, v2
	v_mul_f32_e32 v5, 0x3d000000, v143
	v_mul_f32_e32 v7, 0xbd38aa3b, v143
	v_exp_f32_e32 v7, v7
	v_add_f32_e32 v4, 1.0, v4
	v_rcp_f32_e32 v4, v4
	v_mul_f32_e32 v10, 0x3d000000, v140
	v_mul_f32_e32 v12, 0x3d000000, v135
	v_mul_f32_e32 v3, v142, v4
	v_add_f32_e32 v4, 1.0, v7
	v_rcp_f32_e32 v4, v4
	v_mul_f32_e32 v3, v138, v3
	v_mul_f32_e32 v3, 0x3b800000, v3
	v_med3_f32 v7, v3, s71, v197
	v_mul_f32_e32 v4, v143, v4
	v_mul_f32_e32 v8, 0xbd38aa3b, v144
	v_exp_f32_e32 v8, v8
	v_mul_f32_e32 v3, v139, v4
	v_mul_f32_e32 v3, 0x3b800000, v3
	v_add_f32_e32 v4, 1.0, v8
	v_mul_f32_e32 v9, 0xbd38aa3b, v145
	v_rcp_f32_e32 v4, v4
	v_exp_f32_e32 v9, v9
	v_med3_f32 v3, v3, s71, v197
	v_cvt_pk_fp8_f32 v7, v7, v3
	v_mul_f32_e32 v4, v144, v4
	v_add_f32_e32 v5, 1.0, v9
	v_rcp_f32_e32 v5, v5
	v_mul_f32_e32 v4, v140, v4
	v_mul_f32_e32 v4, 0x3b800000, v4
	v_mul_f32_e32 v5, v145, v5
	v_mul_f32_e32 v3, v141, v5
	v_mul_f32_e32 v3, 0x3b800000, v3
	v_med3_f32 v4, v4, s71, v197
	v_med3_f32 v3, v3, s71, v197
	v_cvt_pk_fp8_f32 v7, v4, v3 op_sel:[0,0,1]
	v_mul_f32_e32 v3, 0xbd38aa3b, v134
	v_exp_f32_e32 v11, v3
	v_mul_f32_e32 v13, 0xbd38aa3b, v135
	v_exp_f32_e32 v13, v13
	v_add_f32_e32 v11, 1.0, v11
	v_rcp_f32_e32 v11, v11
	s_mul_hi_i32 s0, s28, 0x2e8ba2e9
	s_lshr_b32 s1, s0, 31
	s_lshr_b32 s0, s0, 2
	v_mul_f32_e32 v10, v134, v11
	v_add_f32_e32 v11, 1.0, v13
	v_rcp_f32_e32 v11, v11
	v_mul_f32_e32 v10, v130, v10
	v_mul_f32_e32 v10, 0x3b800000, v10
	v_mul_f32_e32 v11, v135, v11
	v_mul_f32_e32 v14, 0xbd38aa3b, v136
	v_exp_f32_e32 v14, v14
	v_mul_f32_e32 v11, v131, v11
	v_mul_f32_e32 v11, 0x3b800000, v11
	v_med3_f32 v10, v10, s71, v197
	v_add_f32_e32 v13, 1.0, v14
	v_mul_f32_e32 v14, 0x3d000000, v137
	v_mul_f32_e32 v15, 0xbd38aa3b, v137
	v_rcp_f32_e32 v13, v13
	v_exp_f32_e32 v15, v15
	v_med3_f32 v11, v11, s71, v197
	v_mul_f32_e32 v16, 0x3d000000, v132
	v_mul_f32_e32 v12, v136, v13
	v_add_f32_e32 v13, 1.0, v15
	v_rcp_f32_e32 v13, v13
	v_cvt_pk_fp8_f32 v10, v10, v11
	s_add_i32 s0, s0, s1
	v_mul_f32_e32 v13, v137, v13
	v_mul_f32_e32 v12, v132, v12
	v_mul_f32_e32 v11, v133, v13
	s_mul_i32 s0, s0, 22
	v_mul_f32_e32 v12, 0x3b800000, v12
	v_mul_f32_e32 v11, 0x3b800000, v11
	s_sub_i32 s0, s28, s0
	v_med3_f32 v12, v12, s71, v197
	v_med3_f32 v11, v11, s71, v197
	v_lshl_add_u32 v6, s74, 8, v159
	v_lshl_or_b32 v2, s0, 7, v183
	v_mov_b64_e32 v[4:5], s[14:15]
	v_cvt_pk_fp8_f32 v10, v12, v11 op_sel:[0,0,1]
	v_mad_i64_i32 v[8:9], s[30:31], v6, s72, v[4:5]
	v_ashrrev_i32_e32 v3, 31, v2
	v_lshl_add_u64 v[8:9], v[8:9], 0, v[2:3]
	s_nop 15
	s_nop 15
	global_store_dword v[8:9], v7, off
	global_store_dword v[8:9], v10, off offset:64
	v_mul_f32_e32 v12, 0xbd38aa3b, v126
	v_mul_f32_e32 v10, 0xbd38aa3b, v127
	v_exp_f32_e32 v12, v12
	v_exp_f32_e32 v10, v10
	v_mul_f32_e32 v14, 0x3d000000, v124
	v_or_b32_e32 v7, 16, v6
	v_add_f32_e32 v8, 1.0, v12
	v_add_f32_e32 v10, 1.0, v10
	v_rcp_f32_e32 v8, v8
	v_rcp_f32_e32 v10, v10
	v_mul_f32_e32 v16, 0x3d000000, v116
	v_mul_f32_e32 v8, v126, v8
	v_mul_f32_e32 v9, v127, v10
	v_mul_f32_e32 v8, v122, v8
	v_mul_f32_e32 v12, 0xbd38aa3b, v128
	v_exp_f32_e32 v12, v12
	v_mul_f32_e32 v8, 0x3b800000, v8
	v_med3_f32 v11, v8, s71, v197
	v_mul_f32_e32 v8, v123, v9
	v_add_f32_e32 v9, 1.0, v12
	v_mul_f32_e32 v13, 0xbd38aa3b, v129
	v_rcp_f32_e32 v9, v9
	v_exp_f32_e32 v13, v13
	v_mul_f32_e32 v8, 0x3b800000, v8
	v_med3_f32 v8, v8, s71, v197
	v_mul_f32_e32 v9, v128, v9
	v_add_f32_e32 v10, 1.0, v13
	v_rcp_f32_e32 v10, v10
	v_cvt_pk_fp8_f32 v11, v11, v8
	v_mul_f32_e32 v9, v124, v9
	v_mul_f32_e32 v10, v129, v10
	v_mul_f32_e32 v8, v125, v10
	v_mul_f32_e32 v9, 0x3b800000, v9
	v_mul_f32_e32 v8, 0x3b800000, v8
	v_med3_f32 v9, v9, s71, v197
	v_med3_f32 v8, v8, s71, v197
	v_cvt_pk_fp8_f32 v11, v9, v8 op_sel:[0,0,1]
	v_mul_f32_e32 v8, 0xbd38aa3b, v118
	v_exp_f32_e32 v12, v8
	v_mad_i64_i32 v[8:9], s[30:31], v7, s72, v[4:5]
	v_add_f32_e32 v7, 1.0, v12
	v_mul_f32_e32 v12, 0x3d000000, v119
	v_mul_f32_e32 v13, 0xbd38aa3b, v119
	v_rcp_f32_e32 v7, v7
	v_exp_f32_e32 v13, v13
	v_lshl_add_u64 v[8:9], v[8:9], 0, v[2:3]
	s_and_b64 vcc, exec, s[12:13]
	v_mul_f32_e32 v7, v118, v7
	v_add_f32_e32 v10, 1.0, v13
	v_rcp_f32_e32 v10, v10
	v_mul_f32_e32 v7, v114, v7
	v_mul_f32_e32 v7, 0x3b800000, v7
	v_mul_f32_e32 v10, v119, v10
	v_mul_f32_e32 v14, 0xbd38aa3b, v120
	v_exp_f32_e32 v14, v14
	v_mul_f32_e32 v10, v115, v10
	v_mul_f32_e32 v10, 0x3b800000, v10
	v_med3_f32 v7, v7, s71, v197
	v_add_f32_e32 v13, 1.0, v14
	v_mul_f32_e32 v14, 0x3d000000, v121
	v_mul_f32_e32 v15, 0xbd38aa3b, v121
	v_rcp_f32_e32 v13, v13
	v_exp_f32_e32 v15, v15
	v_med3_f32 v10, v10, s71, v197
	v_cvt_pk_fp8_f32 v7, v7, v10
	v_mul_f32_e32 v12, v120, v13
	v_add_f32_e32 v13, 1.0, v15
	v_rcp_f32_e32 v13, v13
	v_mul_f32_e32 v12, v116, v12
	v_mul_f32_e32 v12, 0x3b800000, v12
	v_mul_f32_e32 v13, v121, v13
	v_mul_f32_e32 v10, v117, v13
	v_mul_f32_e32 v10, 0x3b800000, v10
	v_med3_f32 v12, v12, s71, v197
	v_med3_f32 v10, v10, s71, v197
	v_cvt_pk_fp8_f32 v7, v12, v10 op_sel:[0,0,1]
	v_mul_f32_e32 v12, 0xbd38aa3b, v110
	v_exp_f32_e32 v12, v12
	global_store_dword v[8:9], v11, off
	global_store_dword v[8:9], v7, off offset:64
	v_mul_f32_e32 v11, 0xbd38aa3b, v111
	v_add_f32_e32 v8, 1.0, v12
	v_rcp_f32_e32 v8, v8
	v_exp_f32_e32 v11, v11
	v_mul_f32_e32 v14, 0x3d000000, v108
	v_mul_f32_e32 v8, v110, v8
	v_add_f32_e32 v10, 1.0, v11
	v_rcp_f32_e32 v10, v10
	v_mul_f32_e32 v8, v106, v8
	v_mul_f32_e32 v8, 0x3b800000, v8
	v_med3_f32 v11, v8, s71, v197
	v_mul_f32_e32 v9, v111, v10
	v_mul_f32_e32 v12, 0xbd38aa3b, v112
	v_exp_f32_e32 v12, v12
	v_mul_f32_e32 v8, v107, v9
	v_mul_f32_e32 v8, 0x3b800000, v8
	v_add_f32_e32 v9, 1.0, v12
	v_mul_f32_e32 v13, 0xbd38aa3b, v113
	v_rcp_f32_e32 v9, v9
	v_exp_f32_e32 v13, v13
	v_med3_f32 v8, v8, s71, v197
	v_cvt_pk_fp8_f32 v11, v11, v8
	v_mul_f32_e32 v9, v112, v9
	v_add_f32_e32 v10, 1.0, v13
	v_rcp_f32_e32 v10, v10
	v_mul_f32_e32 v9, v108, v9
	v_mul_f32_e32 v9, 0x3b800000, v9
	v_mul_f32_e32 v10, v113, v10
	v_mul_f32_e32 v8, v109, v10
	v_mul_f32_e32 v8, 0x3b800000, v8
	v_med3_f32 v9, v9, s71, v197
	v_med3_f32 v8, v8, s71, v197
	v_cvt_pk_fp8_f32 v11, v9, v8 op_sel:[0,0,1]
	v_mul_f32_e32 v8, 0xbd38aa3b, v102
	v_exp_f32_e32 v12, v8
	v_or_b32_e32 v7, 32, v6
	v_mad_i64_i32 v[8:9], s[30:31], v7, s72, v[4:5]
	v_add_f32_e32 v7, 1.0, v12
	v_mul_f32_e32 v12, 0x3d000000, v103
	v_mul_f32_e32 v13, 0xbd38aa3b, v103
	v_rcp_f32_e32 v7, v7
	v_exp_f32_e32 v13, v13
	v_mul_f32_e32 v16, 0x3d000000, v100
	v_mul_f32_e32 v7, v102, v7
	v_add_f32_e32 v10, 1.0, v13
	v_rcp_f32_e32 v10, v10
	v_mul_f32_e32 v7, v98, v7
	v_mul_f32_e32 v7, 0x3b800000, v7
	v_mul_f32_e32 v10, v103, v10
	v_mul_f32_e32 v14, 0xbd38aa3b, v104
	v_exp_f32_e32 v14, v14
	v_mul_f32_e32 v10, v99, v10
	v_mul_f32_e32 v10, 0x3b800000, v10
	v_med3_f32 v7, v7, s71, v197
	v_add_f32_e32 v13, 1.0, v14
	v_mul_f32_e32 v14, 0x3d000000, v105
	v_mul_f32_e32 v15, 0xbd38aa3b, v105
	v_rcp_f32_e32 v13, v13
	v_exp_f32_e32 v15, v15
	v_med3_f32 v10, v10, s71, v197
	v_cvt_pk_fp8_f32 v7, v7, v10
	v_mul_f32_e32 v12, v104, v13
	v_add_f32_e32 v13, 1.0, v15
	v_rcp_f32_e32 v13, v13
	v_mul_f32_e32 v12, v100, v12
	v_mul_f32_e32 v12, 0x3b800000, v12
	v_mul_f32_e32 v13, v105, v13
	v_mul_f32_e32 v10, v101, v13
	v_mul_f32_e32 v10, 0x3b800000, v10
	v_med3_f32 v12, v12, s71, v197
	v_med3_f32 v10, v10, s71, v197
	v_cvt_pk_fp8_f32 v7, v12, v10 op_sel:[0,0,1]
	v_mul_f32_e32 v12, 0xbd38aa3b, v94
	v_exp_f32_e32 v12, v12
	v_lshl_add_u64 v[8:9], v[8:9], 0, v[2:3]
	global_store_dword v[8:9], v11, off
	global_store_dword v[8:9], v7, off offset:64
	v_add_f32_e32 v8, 1.0, v12
	v_mul_f32_e32 v11, 0xbd38aa3b, v95
	v_rcp_f32_e32 v8, v8
	v_exp_f32_e32 v11, v11
	v_mul_f32_e32 v14, 0x3d000000, v92
	v_mul_f32_e32 v8, v94, v8
	v_add_f32_e32 v10, 1.0, v11
	v_rcp_f32_e32 v10, v10
	v_mul_f32_e32 v8, v90, v8
	v_mul_f32_e32 v8, 0x3b800000, v8
	v_med3_f32 v11, v8, s71, v197
	v_mul_f32_e32 v9, v95, v10
	v_mul_f32_e32 v12, 0xbd38aa3b, v96
	v_exp_f32_e32 v12, v12
	v_mul_f32_e32 v8, v91, v9
	v_mul_f32_e32 v8, 0x3b800000, v8
	v_add_f32_e32 v9, 1.0, v12
	v_mul_f32_e32 v13, 0xbd38aa3b, v97
	v_rcp_f32_e32 v9, v9
	v_exp_f32_e32 v13, v13
	v_med3_f32 v8, v8, s71, v197
	v_cvt_pk_fp8_f32 v11, v11, v8
	v_mul_f32_e32 v9, v96, v9
	v_add_f32_e32 v10, 1.0, v13
	v_rcp_f32_e32 v10, v10
	v_mul_f32_e32 v9, v92, v9
	v_mul_f32_e32 v9, 0x3b800000, v9
	v_mul_f32_e32 v10, v97, v10
	v_mul_f32_e32 v8, v93, v10
	v_mul_f32_e32 v8, 0x3b800000, v8
	v_med3_f32 v9, v9, s71, v197
	v_med3_f32 v8, v8, s71, v197
	v_cvt_pk_fp8_f32 v11, v9, v8 op_sel:[0,0,1]
	v_mul_f32_e32 v8, 0xbd38aa3b, v86
	v_exp_f32_e32 v12, v8
	v_or_b32_e32 v7, 48, v6
	v_mad_i64_i32 v[8:9], s[30:31], v7, s72, v[4:5]
	v_add_f32_e32 v7, 1.0, v12
	v_mul_f32_e32 v12, 0x3d000000, v87
	v_mul_f32_e32 v13, 0xbd38aa3b, v87
	v_rcp_f32_e32 v7, v7
	v_exp_f32_e32 v13, v13
	v_mul_f32_e32 v16, 0x3d000000, v84
	v_mul_f32_e32 v7, v86, v7
	v_add_f32_e32 v10, 1.0, v13
	v_rcp_f32_e32 v10, v10
	v_mul_f32_e32 v7, v82, v7
	v_mul_f32_e32 v7, 0x3b800000, v7
	v_mul_f32_e32 v10, v87, v10
	v_mul_f32_e32 v14, 0xbd38aa3b, v88
	v_exp_f32_e32 v14, v14
	v_mul_f32_e32 v10, v83, v10
	v_mul_f32_e32 v10, 0x3b800000, v10
	v_med3_f32 v7, v7, s71, v197
	v_add_f32_e32 v13, 1.0, v14
	v_mul_f32_e32 v14, 0x3d000000, v89
	v_mul_f32_e32 v15, 0xbd38aa3b, v89
	v_rcp_f32_e32 v13, v13
	v_exp_f32_e32 v15, v15
	v_med3_f32 v10, v10, s71, v197
	v_cvt_pk_fp8_f32 v7, v7, v10
	v_mul_f32_e32 v12, v88, v13
	v_add_f32_e32 v13, 1.0, v15
	v_rcp_f32_e32 v13, v13
	v_mul_f32_e32 v12, v84, v12
	v_mul_f32_e32 v12, 0x3b800000, v12
	v_mul_f32_e32 v13, v89, v13
	v_mul_f32_e32 v10, v85, v13
	v_mul_f32_e32 v10, 0x3b800000, v10
	v_med3_f32 v12, v12, s71, v197
	v_med3_f32 v10, v10, s71, v197
	v_cvt_pk_fp8_f32 v7, v12, v10 op_sel:[0,0,1]
	v_mul_f32_e32 v12, 0xbd38aa3b, v78
	v_exp_f32_e32 v12, v12
	v_lshl_add_u64 v[8:9], v[8:9], 0, v[2:3]
	global_store_dword v[8:9], v11, off
	global_store_dword v[8:9], v7, off offset:64
	v_add_f32_e32 v8, 1.0, v12
	v_mul_f32_e32 v11, 0xbd38aa3b, v79
	v_rcp_f32_e32 v8, v8
	v_exp_f32_e32 v11, v11
	v_mul_f32_e32 v14, 0x3d000000, v76
	v_mul_f32_e32 v8, v78, v8
	v_add_f32_e32 v10, 1.0, v11
	v_rcp_f32_e32 v10, v10
	v_mul_f32_e32 v8, v74, v8
	v_mul_f32_e32 v8, 0x3b800000, v8
	v_med3_f32 v11, v8, s71, v197
	v_mul_f32_e32 v9, v79, v10
	v_mul_f32_e32 v12, 0xbd38aa3b, v80
	v_exp_f32_e32 v12, v12
	v_mul_f32_e32 v8, v75, v9
	v_mul_f32_e32 v8, 0x3b800000, v8
	v_add_f32_e32 v9, 1.0, v12
	v_mul_f32_e32 v13, 0xbd38aa3b, v81
	v_rcp_f32_e32 v9, v9
	v_exp_f32_e32 v13, v13
	v_med3_f32 v8, v8, s71, v197
	v_cvt_pk_fp8_f32 v11, v11, v8
	v_mul_f32_e32 v9, v80, v9
	v_add_f32_e32 v10, 1.0, v13
	v_rcp_f32_e32 v10, v10
	v_mul_f32_e32 v9, v76, v9
	v_mul_f32_e32 v9, 0x3b800000, v9
	v_mul_f32_e32 v10, v81, v10
	v_mul_f32_e32 v8, v77, v10
	v_mul_f32_e32 v8, 0x3b800000, v8
	v_med3_f32 v9, v9, s71, v197
	v_med3_f32 v8, v8, s71, v197
	v_cvt_pk_fp8_f32 v11, v9, v8 op_sel:[0,0,1]
	v_mul_f32_e32 v8, 0xbd38aa3b, v70
	v_exp_f32_e32 v12, v8
	v_add_u32_e32 v7, 0x80, v6
	v_mad_i64_i32 v[8:9], s[30:31], v7, s72, v[4:5]
	v_add_f32_e32 v7, 1.0, v12
	v_mul_f32_e32 v12, 0x3d000000, v71
	v_mul_f32_e32 v13, 0xbd38aa3b, v71
	v_rcp_f32_e32 v7, v7
	v_exp_f32_e32 v13, v13
	v_mul_f32_e32 v16, 0x3d000000, v68
	v_mul_f32_e32 v7, v70, v7
	v_add_f32_e32 v10, 1.0, v13
	v_rcp_f32_e32 v10, v10
	v_mul_f32_e32 v7, v66, v7
	v_mul_f32_e32 v7, 0x3b800000, v7
	v_mul_f32_e32 v10, v71, v10
	v_mul_f32_e32 v14, 0xbd38aa3b, v72
	v_exp_f32_e32 v14, v14
	v_mul_f32_e32 v10, v67, v10
	v_mul_f32_e32 v10, 0x3b800000, v10
	v_med3_f32 v7, v7, s71, v197
	v_add_f32_e32 v13, 1.0, v14
	v_mul_f32_e32 v14, 0x3d000000, v73
	v_mul_f32_e32 v15, 0xbd38aa3b, v73
	v_rcp_f32_e32 v13, v13
	v_exp_f32_e32 v15, v15
	v_med3_f32 v10, v10, s71, v197
	v_cvt_pk_fp8_f32 v7, v7, v10
	v_mul_f32_e32 v12, v72, v13
	v_add_f32_e32 v13, 1.0, v15
	v_rcp_f32_e32 v13, v13
	v_mul_f32_e32 v12, v68, v12
	v_mul_f32_e32 v12, 0x3b800000, v12
	v_mul_f32_e32 v13, v73, v13
	v_mul_f32_e32 v10, v69, v13
	v_mul_f32_e32 v10, 0x3b800000, v10
	v_med3_f32 v12, v12, s71, v197
	v_med3_f32 v10, v10, s71, v197
	v_cvt_pk_fp8_f32 v7, v12, v10 op_sel:[0,0,1]
	v_mul_f32_e32 v12, 0xbd38aa3b, v62
	v_exp_f32_e32 v12, v12
	v_lshl_add_u64 v[8:9], v[8:9], 0, v[2:3]
	global_store_dword v[8:9], v11, off
	global_store_dword v[8:9], v7, off offset:64
	v_add_f32_e32 v8, 1.0, v12
	v_mul_f32_e32 v11, 0xbd38aa3b, v63
	v_rcp_f32_e32 v8, v8
	v_exp_f32_e32 v11, v11
	v_mul_f32_e32 v14, 0x3d000000, v60
	v_mul_f32_e32 v8, v62, v8
	v_add_f32_e32 v10, 1.0, v11
	v_rcp_f32_e32 v10, v10
	v_mul_f32_e32 v8, v58, v8
	v_mul_f32_e32 v8, 0x3b800000, v8
	v_med3_f32 v11, v8, s71, v197
	v_mul_f32_e32 v9, v63, v10
	v_mul_f32_e32 v12, 0xbd38aa3b, v64
	v_exp_f32_e32 v12, v12
	v_mul_f32_e32 v8, v59, v9
	v_mul_f32_e32 v8, 0x3b800000, v8
	v_add_f32_e32 v9, 1.0, v12
	v_mul_f32_e32 v13, 0xbd38aa3b, v65
	v_rcp_f32_e32 v9, v9
	v_exp_f32_e32 v13, v13
	v_med3_f32 v8, v8, s71, v197
	v_cvt_pk_fp8_f32 v11, v11, v8
	v_mul_f32_e32 v9, v64, v9
	v_add_f32_e32 v10, 1.0, v13
	v_rcp_f32_e32 v10, v10
	v_mul_f32_e32 v9, v60, v9
	v_mul_f32_e32 v9, 0x3b800000, v9
	v_mul_f32_e32 v10, v65, v10
	v_mul_f32_e32 v8, v61, v10
	v_mul_f32_e32 v8, 0x3b800000, v8
	v_med3_f32 v9, v9, s71, v197
	v_med3_f32 v8, v8, s71, v197
	v_cvt_pk_fp8_f32 v11, v9, v8 op_sel:[0,0,1]
	v_mul_f32_e32 v8, 0xbd38aa3b, v54
	v_exp_f32_e32 v12, v8
	v_add_u32_e32 v7, 0x90, v6
	v_mad_i64_i32 v[8:9], s[30:31], v7, s72, v[4:5]
	v_add_f32_e32 v7, 1.0, v12
	v_mul_f32_e32 v12, 0x3d000000, v55
	v_mul_f32_e32 v13, 0xbd38aa3b, v55
	v_rcp_f32_e32 v7, v7
	v_exp_f32_e32 v13, v13
	v_mul_f32_e32 v16, 0x3d000000, v52
	v_mul_f32_e32 v7, v54, v7
	v_add_f32_e32 v10, 1.0, v13
	v_rcp_f32_e32 v10, v10
	v_mul_f32_e32 v7, v50, v7
	v_mul_f32_e32 v7, 0x3b800000, v7
	v_mul_f32_e32 v10, v55, v10
	v_mul_f32_e32 v14, 0xbd38aa3b, v56
	v_exp_f32_e32 v14, v14
	v_mul_f32_e32 v10, v51, v10
	v_mul_f32_e32 v10, 0x3b800000, v10
	v_med3_f32 v7, v7, s71, v197
	v_add_f32_e32 v13, 1.0, v14
	v_mul_f32_e32 v14, 0x3d000000, v57
	v_mul_f32_e32 v15, 0xbd38aa3b, v57
	v_rcp_f32_e32 v13, v13
	v_exp_f32_e32 v15, v15
	v_med3_f32 v10, v10, s71, v197
	v_cvt_pk_fp8_f32 v7, v7, v10
	v_mul_f32_e32 v12, v56, v13
	v_add_f32_e32 v13, 1.0, v15
	v_rcp_f32_e32 v13, v13
	v_mul_f32_e32 v12, v52, v12
	v_mul_f32_e32 v12, 0x3b800000, v12
	v_mul_f32_e32 v13, v57, v13
	v_mul_f32_e32 v10, v53, v13
	v_mul_f32_e32 v10, 0x3b800000, v10
	v_med3_f32 v12, v12, s71, v197
	v_med3_f32 v10, v10, s71, v197
	v_cvt_pk_fp8_f32 v7, v12, v10 op_sel:[0,0,1]
	v_mul_f32_e32 v12, 0xbd38aa3b, v46
	v_exp_f32_e32 v12, v12
	v_lshl_add_u64 v[8:9], v[8:9], 0, v[2:3]
	global_store_dword v[8:9], v11, off
	global_store_dword v[8:9], v7, off offset:64
	v_add_f32_e32 v8, 1.0, v12
	v_mul_f32_e32 v11, 0xbd38aa3b, v47
	v_rcp_f32_e32 v8, v8
	v_exp_f32_e32 v11, v11
	v_mul_f32_e32 v14, 0x3d000000, v44
	v_mul_f32_e32 v8, v46, v8
	v_add_f32_e32 v10, 1.0, v11
	v_rcp_f32_e32 v10, v10
	v_mul_f32_e32 v8, v42, v8
	v_mul_f32_e32 v8, 0x3b800000, v8
	v_med3_f32 v11, v8, s71, v197
	v_mul_f32_e32 v9, v47, v10
	v_mul_f32_e32 v12, 0xbd38aa3b, v48
	v_exp_f32_e32 v12, v12
	v_mul_f32_e32 v8, v43, v9
	v_mul_f32_e32 v8, 0x3b800000, v8
	v_add_f32_e32 v9, 1.0, v12
	v_mul_f32_e32 v13, 0xbd38aa3b, v49
	v_rcp_f32_e32 v9, v9
	v_exp_f32_e32 v13, v13
	v_med3_f32 v8, v8, s71, v197
	v_cvt_pk_fp8_f32 v11, v11, v8
	v_mul_f32_e32 v9, v48, v9
	v_add_f32_e32 v10, 1.0, v13
	v_rcp_f32_e32 v10, v10
	v_mul_f32_e32 v9, v44, v9
	v_mul_f32_e32 v9, 0x3b800000, v9
	v_mul_f32_e32 v10, v49, v10
	v_mul_f32_e32 v8, v45, v10
	v_mul_f32_e32 v8, 0x3b800000, v8
	v_med3_f32 v9, v9, s71, v197
	v_med3_f32 v8, v8, s71, v197
	v_cvt_pk_fp8_f32 v11, v9, v8 op_sel:[0,0,1]
	v_mul_f32_e32 v8, 0xbd38aa3b, v38
	v_exp_f32_e32 v12, v8
	v_add_u32_e32 v7, 0xa0, v6
	v_mad_i64_i32 v[8:9], s[30:31], v7, s72, v[4:5]
	v_add_f32_e32 v7, 1.0, v12
	v_mul_f32_e32 v12, 0x3d000000, v39
	v_mul_f32_e32 v13, 0xbd38aa3b, v39
	v_rcp_f32_e32 v7, v7
	v_exp_f32_e32 v13, v13
	v_mul_f32_e32 v7, v38, v7
	v_add_f32_e32 v10, 1.0, v13
	v_rcp_f32_e32 v10, v10
	v_mul_f32_e32 v7, v34, v7
	v_mul_f32_e32 v7, 0x3b800000, v7
	v_mul_f32_e32 v10, v39, v10
	v_mul_f32_e32 v14, 0xbd38aa3b, v40
	v_exp_f32_e32 v14, v14
	v_mul_f32_e32 v10, v35, v10
	v_mul_f32_e32 v10, 0x3b800000, v10
	v_med3_f32 v7, v7, s71, v197
	v_add_f32_e32 v13, 1.0, v14
	v_mul_f32_e32 v14, 0x3d000000, v41
	v_mul_f32_e32 v15, 0xbd38aa3b, v41
	v_rcp_f32_e32 v13, v13
	v_exp_f32_e32 v15, v15
	v_med3_f32 v10, v10, s71, v197
	v_cvt_pk_fp8_f32 v7, v7, v10
	v_mul_f32_e32 v12, v40, v13
	v_add_f32_e32 v13, 1.0, v15
	v_rcp_f32_e32 v13, v13
	v_mul_f32_e32 v12, v36, v12
	v_mul_f32_e32 v12, 0x3b800000, v12
	v_mul_f32_e32 v13, v41, v13
	v_mul_f32_e32 v10, v37, v13
	v_mul_f32_e32 v10, 0x3b800000, v10
	v_med3_f32 v12, v12, s71, v197
	v_med3_f32 v10, v10, s71, v197
	v_cvt_pk_fp8_f32 v7, v12, v10 op_sel:[0,0,1]
	v_lshl_add_u64 v[8:9], v[8:9], 0, v[2:3]
	v_mul_f32_e32 v10, 0x3d000000, v30
	global_store_dword v[8:9], v11, off
	global_store_dword v[8:9], v7, off offset:64
	v_mul_f32_e32 v12, 0xbd38aa3b, v30
	v_mul_f32_e32 v9, 0xbd38aa3b, v31
	v_exp_f32_e32 v12, v12
	v_exp_f32_e32 v9, v9
	v_add_f32_e32 v7, 1.0, v12
	v_add_f32_e32 v9, 1.0, v9
	v_rcp_f32_e32 v7, v7
	v_rcp_f32_e32 v9, v9
	v_add_u32_e32 v6, 0xb0, v6
	v_mul_f32_e32 v7, v30, v7
	v_mul_f32_e32 v8, v31, v9
	v_mul_f32_e32 v7, v26, v7
	v_mul_f32_e32 v11, 0xbd38aa3b, v32
	v_exp_f32_e32 v11, v11
	v_mul_f32_e32 v8, v27, v8
	v_mul_f32_e32 v7, 0x3b800000, v7
	v_add_f32_e32 v10, 1.0, v11
	v_mul_f32_e32 v12, 0xbd38aa3b, v33
	v_rcp_f32_e32 v10, v10
	v_exp_f32_e32 v12, v12
	v_mul_f32_e32 v8, 0x3b800000, v8
	v_med3_f32 v7, v7, s71, v197
	v_mul_f32_e32 v9, v32, v10
	v_add_f32_e32 v10, 1.0, v12
	v_rcp_f32_e32 v10, v10
	v_med3_f32 v8, v8, s71, v197
	v_cvt_pk_fp8_f32 v7, v7, v8
	v_mul_f32_e32 v12, 0x3d000000, v29
	v_mul_f32_e32 v10, v33, v10
	v_mul_f32_e32 v11, 0xbd38aa3b, v22
	v_mul_f32_e32 v9, v28, v9
	v_mul_f32_e32 v10, v29, v10
	v_exp_f32_e32 v11, v11
	v_mul_f32_e32 v9, 0x3b800000, v9
	v_mul_f32_e32 v10, 0x3b800000, v10
	v_med3_f32 v9, v9, s71, v197
	v_med3_f32 v10, v10, s71, v197
	v_cvt_pk_fp8_f32 v7, v9, v10 op_sel:[0,0,1]
	v_mul_f32_e32 v10, 0x3d000000, v23
	v_add_f32_e32 v9, 1.0, v11
	v_mul_f32_e32 v11, 0xbd38aa3b, v23
	v_rcp_f32_e32 v9, v9
	v_exp_f32_e32 v11, v11
	v_mad_i64_i32 v[4:5], s[30:31], v6, s72, v[4:5]
	v_mul_f32_e32 v8, v22, v9
	v_add_f32_e32 v9, 1.0, v11
	v_rcp_f32_e32 v9, v9
	v_mul_f32_e32 v8, v18, v8
	v_mul_f32_e32 v8, 0x3b800000, v8
	v_mul_f32_e32 v9, v23, v9
	v_mul_f32_e32 v12, 0xbd38aa3b, v24
	v_exp_f32_e32 v12, v12
	v_mul_f32_e32 v9, v19, v9
	v_mul_f32_e32 v9, 0x3b800000, v9
	v_med3_f32 v8, v8, s71, v197
	v_add_f32_e32 v11, 1.0, v12
	v_mul_f32_e32 v13, 0xbd38aa3b, v25
	v_rcp_f32_e32 v11, v11
	v_exp_f32_e32 v13, v13
	v_med3_f32 v9, v9, s71, v197
	v_cvt_pk_fp8_f32 v8, v8, v9
	v_mul_f32_e32 v10, v24, v11
	v_add_f32_e32 v11, 1.0, v13
	v_rcp_f32_e32 v11, v11
	v_mul_f32_e32 v10, v20, v10
	v_mul_f32_e32 v10, 0x3b800000, v10
	v_mul_f32_e32 v11, v25, v11
	v_mul_f32_e32 v9, v21, v11
	v_mul_f32_e32 v9, 0x3b800000, v9
	v_med3_f32 v10, v10, s71, v197
	v_med3_f32 v9, v9, s71, v197
	v_cvt_pk_fp8_f32 v8, v10, v9 op_sel:[0,0,1]
	v_lshl_add_u64 v[2:3], v[4:5], 0, v[2:3]
	v_mov_b32_e32 v200, v161
	v_mov_b32_e32 v158, v163
	v_mov_b32_e32 v160, v198
	v_mov_b32_e32 v162, v199
	s_mov_b32 s28, s24
	s_mov_b32 s74, s73
	s_mov_b64 s[30:31], s[26:27]
	global_store_dword v[2:3], v7, off
	global_store_dword v[2:3], v8, off offset:64
	s_cbranch_vccz .LBB0_2875
	s_waitcnt vmcnt(0)
	s_cmpk_gt_u32 s39, 0xff
	s_cbranch_scc1 .LBB0_2882
	s_barrier

.LBB0_5616:
	ds_read2_b32 v[2:3], v178 offset1:16
	s_add_u32 s0, s3, s24
	s_addc_u32 s1, s30, s25
	s_add_u32 s0, s0, 0x1b3c3200
	ds_read2_b32 v[168:169], v178 offset0:32 offset1:48
	s_waitcnt lgkmcnt(0)
	v_lshl_add_u32 v161, v2, 10, v1
	v_lshl_add_u32 v163, v3, 10, v176
	ds_read_b128 v[2:5], v179
	ds_read_b128 v[6:9], v184
	ds_read_b128 v[10:13], v185
	ds_read_b128 v[14:17], v186
	s_addc_u32 s1, s1, 0
	s_add_u32 s2, s62, s24
	s_addc_u32 s4, s63, s25
	s_cmpk_eq_i32 s24, 0x300
	s_cselect_b64 vcc, -1, 0
	s_and_b64 s[26:27], vcc, exec
	v_lshl_add_u32 v198, v168, 10, v1
	v_lshl_add_u32 v199, v169, 10, v176
	v_cndmask_b32_e32 v150, v200, v161, vcc
	s_cselect_b32 s29, s11, s1
	s_cselect_b32 s28, s10, s0
	v_cndmask_b32_e32 v172, v158, v163, vcc
	v_cndmask_b32_e32 v201, v160, v198, vcc
	s_cselect_b32 s27, s19, s4
	s_cselect_b32 s26, s61, s2
	v_cndmask_b32_e32 v219, v162, v199, vcc
	v_lshl_add_u64 v[168:169], v[166:167], 0, s[24:25]
	s_add_i32 m0, s38, 0xc000
	ds_read_b128 v[202:205], v196
	ds_read_b128 v[206:209], v196 offset:1024
	ds_read_b128 v[210:213], v196 offset:2048
	ds_read_b128 v[214:217], v196 offset:3072
	ds_read_b128 v[220:223], v196 offset:4096
	ds_read_b128 v[224:227], v196 offset:5120
	ds_read_b128 v[228:231], v196 offset:6144
	ds_read_b128 v[232:235], v196 offset:7168
	global_load_lds_dwordx4 v[168:169], off
	v_lshl_add_u64 v[168:169], v[164:165], 0, s[24:25]
	s_add_i32 m0, s38, 0xe000
	s_nop 0
	global_load_lds_dwordx4 v[168:169], off
	s_waitcnt lgkmcnt(8)
	s_barrier
	s_waitcnt lgkmcnt(0)
	s_setprio 1
	s_waitcnt lgkmcnt(0)
	v_mfma_f32_16x16x128_f8f6f4 v[142:145], v[2:9], v[202:209], v[142:145]
	v_mfma_f32_16x16x128_f8f6f4 v[138:141], v[10:17], v[202:209], v[138:141]
	v_mfma_f32_16x16x128_f8f6f4 v[126:129], v[2:9], v[210:217], v[126:129]
	v_mfma_f32_16x16x128_f8f6f4 v[122:125], v[10:17], v[210:217], v[122:125]
	v_mfma_f32_16x16x128_f8f6f4 v[110:113], v[2:9], v[220:227], v[110:113]
	v_mfma_f32_16x16x128_f8f6f4 v[106:109], v[10:17], v[220:227], v[106:109]
	v_mfma_f32_16x16x128_f8f6f4 v[94:97], v[2:9], v[228:235], v[94:97]
	v_mfma_f32_16x16x128_f8f6f4 v[90:93], v[10:17], v[228:235], v[90:93]
	s_setprio 0
	s_barrier
	s_mov_b32 m0, s39
	v_lshl_add_u64 v[168:169], s[26:27], 0, v[148:149]
	ds_read_b128 v[236:239], v180
	ds_read_b128 v[240:243], v187
	ds_read_b128 v[244:247], v188
	ds_read_b128 v[248:251], v189
	global_load_lds_dwordx4 v[168:169], off
	v_lshl_add_u64 v[170:171], s[26:27], 0, v[146:147]
	s_mov_b32 m0, s40
	s_nop 0
	global_load_lds_dwordx4 v[170:171], off
	s_barrier
	s_waitcnt lgkmcnt(0)
	s_setprio 1
	s_waitcnt lgkmcnt(0)
	v_mfma_f32_16x16x128_f8f6f4 v[134:137], v[236:243], v[202:209], v[134:137]
	v_mfma_f32_16x16x128_f8f6f4 v[130:133], v[244:251], v[202:209], v[130:133]
	v_mfma_f32_16x16x128_f8f6f4 v[118:121], v[236:243], v[210:217], v[118:121]
	v_mfma_f32_16x16x128_f8f6f4 v[114:117], v[244:251], v[210:217], v[114:117]
	v_mfma_f32_16x16x128_f8f6f4 v[102:105], v[236:243], v[220:227], v[102:105]
	v_mfma_f32_16x16x128_f8f6f4 v[98:101], v[244:251], v[220:227], v[98:101]
	v_mfma_f32_16x16x128_f8f6f4 v[86:89], v[236:243], v[228:235], v[86:89]
	v_mfma_f32_16x16x128_f8f6f4 v[82:85], v[244:251], v[228:235], v[82:85]
	s_setprio 0
	s_mov_b32 m0, s38
	s_barrier
	ds_read_b128 v[202:205], v196 offset:16384
	ds_read_b128 v[206:209], v196 offset:17408
	ds_read_b128 v[210:213], v196 offset:18432
	ds_read_b128 v[214:217], v196 offset:19456
	ds_read_b128 v[220:223], v196 offset:20480
	ds_read_b128 v[224:227], v196 offset:21504
	ds_read_b128 v[228:231], v196 offset:22528
	ds_read_b128 v[232:235], v196 offset:23552
	global_load_lds_dwordx4 v150, s[28:29]
	s_mov_b32 m0, s41
	v_mov_b32_e32 v173, v151
	global_load_lds_dwordx4 v172, s[28:29]
	s_barrier
	s_waitcnt lgkmcnt(0)
	v_lshl_add_u64 v[174:175], s[28:29], 0, v[150:151]
	v_lshl_add_u64 v[172:173], s[28:29], 0, v[172:173]
	s_setprio 1
	s_waitcnt lgkmcnt(0)
	v_mfma_f32_16x16x128_f8f6f4 v[78:81], v[2:9], v[202:209], v[78:81]
	v_mfma_f32_16x16x128_f8f6f4 v[74:77], v[10:17], v[202:209], v[74:77]
	v_mfma_f32_16x16x128_f8f6f4 v[62:65], v[2:9], v[210:217], v[62:65]
	v_mfma_f32_16x16x128_f8f6f4 v[58:61], v[10:17], v[210:217], v[58:61]
	v_mfma_f32_16x16x128_f8f6f4 v[46:49], v[2:9], v[220:227], v[46:49]
	v_mfma_f32_16x16x128_f8f6f4 v[42:45], v[10:17], v[220:227], v[42:45]
	v_mfma_f32_16x16x128_f8f6f4 v[30:33], v[2:9], v[228:235], v[30:33]
	v_mfma_f32_16x16x128_f8f6f4 v[26:29], v[10:17], v[228:235], v[26:29]
	s_setprio 0
	s_barrier
	s_add_u32 s66, s26, 0x20000
	s_addc_u32 s67, s27, 0
	s_mov_b32 m0, s42
	v_lshl_add_u64 v[2:3], s[66:67], 0, v[148:149]
	global_load_lds_dwordx4 v[2:3], off
	v_lshl_add_u64 v[2:3], s[66:67], 0, v[146:147]
	s_mov_b32 m0, s43
	s_nop 0
	global_load_lds_dwordx4 v[2:3], off
	s_waitcnt vmcnt(6)
	s_barrier
	s_setprio 1
	v_mfma_f32_16x16x128_f8f6f4 v[70:73], v[236:243], v[202:209], v[70:73]
	v_mfma_f32_16x16x128_f8f6f4 v[66:69], v[244:251], v[202:209], v[66:69]
	v_mfma_f32_16x16x128_f8f6f4 v[54:57], v[236:243], v[210:217], v[54:57]
	v_mfma_f32_16x16x128_f8f6f4 v[50:53], v[244:251], v[210:217], v[50:53]
	v_mfma_f32_16x16x128_f8f6f4 v[38:41], v[236:243], v[220:227], v[38:41]
	v_mfma_f32_16x16x128_f8f6f4 v[34:37], v[244:251], v[220:227], v[34:37]
	v_mfma_f32_16x16x128_f8f6f4 v[22:25], v[236:243], v[228:235], v[22:25]
	v_mfma_f32_16x16x128_f8f6f4 v[18:21], v[244:251], v[228:235], v[18:21]
	s_setprio 0
	s_barrier
	ds_read_b128 v[2:5], v181
	ds_read_b128 v[6:9], v190
	ds_read_b128 v[10:13], v191
	ds_read_b128 v[14:17], v192
	s_mov_b32 m0, s44
	ds_read_b128 v[202:205], v196 offset:32768
	ds_read_b128 v[206:209], v196 offset:33792
	ds_read_b128 v[210:213], v196 offset:34816
	ds_read_b128 v[214:217], v196 offset:35840
	ds_read_b128 v[220:223], v196 offset:36864
	ds_read_b128 v[224:227], v196 offset:37888
	ds_read_b128 v[228:231], v196 offset:38912
	ds_read_b128 v[232:235], v196 offset:39936
	global_load_lds_dwordx4 v201, s[28:29]
	s_mov_b32 m0, s45
	s_nop 0
	global_load_lds_dwordx4 v219, s[28:29]
	s_waitcnt lgkmcnt(8)
	s_barrier
	s_waitcnt lgkmcnt(0)
	s_setprio 1
	s_waitcnt lgkmcnt(0)
	v_mfma_f32_16x16x128_f8f6f4 v[142:145], v[2:9], v[202:209], v[142:145]
	v_mfma_f32_16x16x128_f8f6f4 v[138:141], v[10:17], v[202:209], v[138:141]
	v_mfma_f32_16x16x128_f8f6f4 v[126:129], v[2:9], v[210:217], v[126:129]
	v_mfma_f32_16x16x128_f8f6f4 v[122:125], v[10:17], v[210:217], v[122:125]
	v_mfma_f32_16x16x128_f8f6f4 v[110:113], v[2:9], v[220:227], v[110:113]
	v_mfma_f32_16x16x128_f8f6f4 v[106:109], v[10:17], v[220:227], v[106:109]
	v_mfma_f32_16x16x128_f8f6f4 v[94:97], v[2:9], v[228:235], v[94:97]
	v_mfma_f32_16x16x128_f8f6f4 v[90:93], v[10:17], v[228:235], v[90:93]
	s_setprio 0
	s_barrier
	s_mov_b32 m0, s47
	v_lshl_add_u64 v[168:169], v[168:169], 0, s[14:15]
	ds_read_b128 v[236:239], v182
	ds_read_b128 v[240:243], v193
	ds_read_b128 v[244:247], v194
	ds_read_b128 v[248:251], v195
	global_load_lds_dwordx4 v[168:169], off
	v_lshl_add_u64 v[168:169], v[170:171], 0, s[14:15]
	s_mov_b32 m0, s48
	s_nop 0
	global_load_lds_dwordx4 v[168:169], off
	s_barrier
	s_waitcnt lgkmcnt(0)
	s_setprio 1
	s_waitcnt lgkmcnt(0)
	v_mfma_f32_16x16x128_f8f6f4 v[134:137], v[236:243], v[202:209], v[134:137]
	v_mfma_f32_16x16x128_f8f6f4 v[130:133], v[244:251], v[202:209], v[130:133]
	v_mfma_f32_16x16x128_f8f6f4 v[118:121], v[236:243], v[210:217], v[118:121]
	v_mfma_f32_16x16x128_f8f6f4 v[114:117], v[244:251], v[210:217], v[114:117]
	v_mfma_f32_16x16x128_f8f6f4 v[102:105], v[236:243], v[220:227], v[102:105]
	v_mfma_f32_16x16x128_f8f6f4 v[98:101], v[244:251], v[220:227], v[98:101]
	v_mfma_f32_16x16x128_f8f6f4 v[86:89], v[236:243], v[228:235], v[86:89]
	v_mfma_f32_16x16x128_f8f6f4 v[82:85], v[244:251], v[228:235], v[82:85]
	s_setprio 0
	s_mov_b32 m0, s49
	v_lshl_add_u64 v[168:169], v[174:175], 0, s[14:15]
	s_barrier
	ds_read_b128 v[202:205], v196 offset:49152
	ds_read_b128 v[206:209], v196 offset:50176
	ds_read_b128 v[210:213], v196 offset:51200
	ds_read_b128 v[214:217], v196 offset:52224
	ds_read_b128 v[220:223], v196 offset:53248
	ds_read_b128 v[224:227], v196 offset:54272
	ds_read_b128 v[228:231], v196 offset:55296
	ds_read_b128 v[232:235], v196 offset:56320
	global_load_lds_dwordx4 v[168:169], off
	v_lshl_add_u64 v[168:169], v[172:173], 0, s[14:15]
	s_mov_b32 m0, s50
	s_nop 0
	global_load_lds_dwordx4 v[168:169], off
	s_barrier
	s_waitcnt lgkmcnt(0)
	s_setprio 1
	s_waitcnt lgkmcnt(0)
	v_mfma_f32_16x16x128_f8f6f4 v[78:81], v[2:9], v[202:209], v[78:81]
	v_mfma_f32_16x16x128_f8f6f4 v[74:77], v[10:17], v[202:209], v[74:77]
	v_mfma_f32_16x16x128_f8f6f4 v[62:65], v[2:9], v[210:217], v[62:65]
	v_mfma_f32_16x16x128_f8f6f4 v[58:61], v[10:17], v[210:217], v[58:61]
	v_mfma_f32_16x16x128_f8f6f4 v[46:49], v[2:9], v[220:227], v[46:49]
	v_mfma_f32_16x16x128_f8f6f4 v[42:45], v[10:17], v[220:227], v[42:45]
	v_mfma_f32_16x16x128_f8f6f4 v[30:33], v[2:9], v[228:235], v[30:33]
	v_mfma_f32_16x16x128_f8f6f4 v[26:29], v[10:17], v[228:235], v[26:29]
	s_setprio 0
	s_barrier
	s_add_u32 s26, s26, 0x20080
	s_addc_u32 s27, s27, 0
	s_mov_b32 m0, s51
	v_lshl_add_u64 v[2:3], s[26:27], 0, v[148:149]
	global_load_lds_dwordx4 v[2:3], off
	v_lshl_add_u64 v[2:3], s[26:27], 0, v[146:147]
	s_mov_b32 m0, s52
	s_nop 0
	global_load_lds_dwordx4 v[2:3], off
	s_waitcnt vmcnt(6)
	s_barrier
	s_setprio 1
	v_mfma_f32_16x16x128_f8f6f4 v[70:73], v[236:243], v[202:209], v[70:73]
	v_mfma_f32_16x16x128_f8f6f4 v[66:69], v[244:251], v[202:209], v[66:69]
	v_mfma_f32_16x16x128_f8f6f4 v[54:57], v[236:243], v[210:217], v[54:57]
	v_mfma_f32_16x16x128_f8f6f4 v[50:53], v[244:251], v[210:217], v[50:53]
	v_mfma_f32_16x16x128_f8f6f4 v[38:41], v[236:243], v[220:227], v[38:41]
	v_mfma_f32_16x16x128_f8f6f4 v[34:37], v[244:251], v[220:227], v[34:37]
	v_mfma_f32_16x16x128_f8f6f4 v[22:25], v[236:243], v[228:235], v[22:25]
	v_mfma_f32_16x16x128_f8f6f4 v[18:21], v[244:251], v[228:235], v[18:21]
	s_setprio 0
	s_add_i32 s64, s64, 2
	s_add_u32 s24, s24, 0x100
	s_addc_u32 s25, s25, 0
	s_cmp_gt_u32 s64, 5
	s_barrier
	s_cbranch_scc0 .LBB0_5616
	v_mul_f32_e32 v2, 0xbd38aa3b, v142
	v_exp_f32_e32 v4, v2
	v_mul_f32_e32 v5, 0x3d000000, v143
	v_mul_f32_e32 v7, 0xbd38aa3b, v143
	v_exp_f32_e32 v7, v7
	v_add_f32_e32 v4, 1.0, v4
	v_rcp_f32_e32 v4, v4
	v_mul_f32_e32 v10, 0x3d000000, v140
	v_mul_f32_e32 v12, 0x3d000000, v135
	v_mul_f32_e32 v3, v142, v4
	v_add_f32_e32 v4, 1.0, v7
	v_rcp_f32_e32 v4, v4
	v_mul_f32_e32 v3, v138, v3
	v_mul_f32_e32 v3, 0x3b800000, v3
	v_med3_f32 v7, v3, s55, v197
	v_mul_f32_e32 v4, v143, v4
	v_mul_f32_e32 v8, 0xbd38aa3b, v144
	v_exp_f32_e32 v8, v8
	v_mul_f32_e32 v3, v139, v4
	v_mul_f32_e32 v3, 0x3b800000, v3
	v_add_f32_e32 v4, 1.0, v8
	v_mul_f32_e32 v9, 0xbd38aa3b, v145
	v_rcp_f32_e32 v4, v4
	v_exp_f32_e32 v9, v9
	v_med3_f32 v3, v3, s55, v197
	v_cvt_pk_fp8_f32 v7, v7, v3
	v_mul_f32_e32 v4, v144, v4
	v_add_f32_e32 v5, 1.0, v9
	v_rcp_f32_e32 v5, v5
	v_mul_f32_e32 v4, v140, v4
	v_mul_f32_e32 v4, 0x3b800000, v4
	v_mul_f32_e32 v5, v145, v5
	v_mul_f32_e32 v3, v141, v5
	v_mul_f32_e32 v3, 0x3b800000, v3
	v_med3_f32 v4, v4, s55, v197
	v_med3_f32 v3, v3, s55, v197
	v_cvt_pk_fp8_f32 v7, v4, v3 op_sel:[0,0,1]
	v_mul_f32_e32 v3, 0xbd38aa3b, v134
	v_exp_f32_e32 v11, v3
	v_mul_f32_e32 v13, 0xbd38aa3b, v135
	v_exp_f32_e32 v13, v13
	v_add_f32_e32 v11, 1.0, v11
	v_rcp_f32_e32 v11, v11
	s_mul_hi_i32 s0, s22, 0x2e8ba2e9
	s_lshr_b32 s1, s0, 31
	s_lshr_b32 s0, s0, 2
	v_mul_f32_e32 v10, v134, v11
	v_add_f32_e32 v11, 1.0, v13
	v_rcp_f32_e32 v11, v11
	v_mul_f32_e32 v10, v130, v10
	v_mul_f32_e32 v10, 0x3b800000, v10
	v_mul_f32_e32 v11, v135, v11
	v_mul_f32_e32 v14, 0xbd38aa3b, v136
	v_exp_f32_e32 v14, v14
	v_mul_f32_e32 v11, v131, v11
	v_mul_f32_e32 v11, 0x3b800000, v11
	v_med3_f32 v10, v10, s55, v197
	v_add_f32_e32 v13, 1.0, v14
	v_mul_f32_e32 v14, 0x3d000000, v137
	v_mul_f32_e32 v15, 0xbd38aa3b, v137
	v_rcp_f32_e32 v13, v13
	v_exp_f32_e32 v15, v15
	v_med3_f32 v11, v11, s55, v197
	v_mul_f32_e32 v16, 0x3d000000, v132
	v_mul_f32_e32 v12, v136, v13
	v_add_f32_e32 v13, 1.0, v15
	v_rcp_f32_e32 v13, v13
	v_cvt_pk_fp8_f32 v10, v10, v11
	s_add_i32 s0, s0, s1
	v_mul_f32_e32 v13, v137, v13
	v_mul_f32_e32 v12, v132, v12
	v_mul_f32_e32 v11, v133, v13
	s_mul_i32 s0, s0, 22
	v_mul_f32_e32 v12, 0x3b800000, v12
	v_mul_f32_e32 v11, 0x3b800000, v11
	s_sub_i32 s0, s22, s0
	v_med3_f32 v12, v12, s55, v197
	v_med3_f32 v11, v11, s55, v197
	v_lshl_add_u32 v6, s60, 8, v159
	v_lshl_or_b32 v2, s0, 7, v183
	v_mov_b64_e32 v[4:5], s[12:13]
	v_cvt_pk_fp8_f32 v10, v12, v11 op_sel:[0,0,1]
	v_mad_i64_i32 v[8:9], s[24:25], v6, s58, v[4:5]
	v_ashrrev_i32_e32 v3, 31, v2
	v_lshl_add_u64 v[8:9], v[8:9], 0, v[2:3]
	s_nop 15
	s_nop 15
	global_store_dword v[8:9], v7, off
	global_store_dword v[8:9], v10, off offset:64
	v_mul_f32_e32 v12, 0xbd38aa3b, v126
	v_mul_f32_e32 v10, 0xbd38aa3b, v127
	v_exp_f32_e32 v12, v12
	v_exp_f32_e32 v10, v10
	v_mul_f32_e32 v14, 0x3d000000, v124
	v_or_b32_e32 v7, 16, v6
	v_add_f32_e32 v8, 1.0, v12
	v_add_f32_e32 v10, 1.0, v10
	v_rcp_f32_e32 v8, v8
	v_rcp_f32_e32 v10, v10
	v_mul_f32_e32 v16, 0x3d000000, v116
	v_mul_f32_e32 v8, v126, v8
	v_mul_f32_e32 v9, v127, v10
	v_mul_f32_e32 v8, v122, v8
	v_mul_f32_e32 v12, 0xbd38aa3b, v128
	v_exp_f32_e32 v12, v12
	v_mul_f32_e32 v8, 0x3b800000, v8
	v_med3_f32 v11, v8, s55, v197
	v_mul_f32_e32 v8, v123, v9
	v_add_f32_e32 v9, 1.0, v12
	v_mul_f32_e32 v13, 0xbd38aa3b, v129
	v_rcp_f32_e32 v9, v9
	v_exp_f32_e32 v13, v13
	v_mul_f32_e32 v8, 0x3b800000, v8
	v_med3_f32 v8, v8, s55, v197
	v_mul_f32_e32 v9, v128, v9
	v_add_f32_e32 v10, 1.0, v13
	v_rcp_f32_e32 v10, v10
	v_cvt_pk_fp8_f32 v11, v11, v8
	v_mul_f32_e32 v9, v124, v9
	v_mul_f32_e32 v10, v129, v10
	v_mul_f32_e32 v8, v125, v10
	v_mul_f32_e32 v9, 0x3b800000, v9
	v_mul_f32_e32 v8, 0x3b800000, v8
	v_med3_f32 v9, v9, s55, v197
	v_med3_f32 v8, v8, s55, v197
	v_cvt_pk_fp8_f32 v11, v9, v8 op_sel:[0,0,1]
	v_mul_f32_e32 v8, 0xbd38aa3b, v118
	v_exp_f32_e32 v12, v8
	v_mad_i64_i32 v[8:9], s[24:25], v7, s58, v[4:5]
	v_add_f32_e32 v7, 1.0, v12
	v_mul_f32_e32 v12, 0x3d000000, v119
	v_mul_f32_e32 v13, 0xbd38aa3b, v119
	v_rcp_f32_e32 v7, v7
	v_exp_f32_e32 v13, v13
	v_lshl_add_u64 v[8:9], v[8:9], 0, v[2:3]
	s_and_b64 vcc, exec, s[8:9]
	v_mul_f32_e32 v7, v118, v7
	v_add_f32_e32 v10, 1.0, v13
	v_rcp_f32_e32 v10, v10
	v_mul_f32_e32 v7, v114, v7
	v_mul_f32_e32 v7, 0x3b800000, v7
	v_mul_f32_e32 v10, v119, v10
	v_mul_f32_e32 v14, 0xbd38aa3b, v120
	v_exp_f32_e32 v14, v14
	v_mul_f32_e32 v10, v115, v10
	v_mul_f32_e32 v10, 0x3b800000, v10
	v_med3_f32 v7, v7, s55, v197
	v_add_f32_e32 v13, 1.0, v14
	v_mul_f32_e32 v14, 0x3d000000, v121
	v_mul_f32_e32 v15, 0xbd38aa3b, v121
	v_rcp_f32_e32 v13, v13
	v_exp_f32_e32 v15, v15
	v_med3_f32 v10, v10, s55, v197
	v_cvt_pk_fp8_f32 v7, v7, v10
	v_mul_f32_e32 v12, v120, v13
	v_add_f32_e32 v13, 1.0, v15
	v_rcp_f32_e32 v13, v13
	v_mul_f32_e32 v12, v116, v12
	v_mul_f32_e32 v12, 0x3b800000, v12
	v_mul_f32_e32 v13, v121, v13
	v_mul_f32_e32 v10, v117, v13
	v_mul_f32_e32 v10, 0x3b800000, v10
	v_med3_f32 v12, v12, s55, v197
	v_med3_f32 v10, v10, s55, v197
	v_cvt_pk_fp8_f32 v7, v12, v10 op_sel:[0,0,1]
	v_mul_f32_e32 v12, 0xbd38aa3b, v110
	v_exp_f32_e32 v12, v12
	global_store_dword v[8:9], v11, off
	global_store_dword v[8:9], v7, off offset:64
	v_mul_f32_e32 v11, 0xbd38aa3b, v111
	v_add_f32_e32 v8, 1.0, v12
	v_rcp_f32_e32 v8, v8
	v_exp_f32_e32 v11, v11
	v_mul_f32_e32 v14, 0x3d000000, v108
	v_mul_f32_e32 v8, v110, v8
	v_add_f32_e32 v10, 1.0, v11
	v_rcp_f32_e32 v10, v10
	v_mul_f32_e32 v8, v106, v8
	v_mul_f32_e32 v8, 0x3b800000, v8
	v_med3_f32 v11, v8, s55, v197
	v_mul_f32_e32 v9, v111, v10
	v_mul_f32_e32 v12, 0xbd38aa3b, v112
	v_exp_f32_e32 v12, v12
	v_mul_f32_e32 v8, v107, v9
	v_mul_f32_e32 v8, 0x3b800000, v8
	v_add_f32_e32 v9, 1.0, v12
	v_mul_f32_e32 v13, 0xbd38aa3b, v113
	v_rcp_f32_e32 v9, v9
	v_exp_f32_e32 v13, v13
	v_med3_f32 v8, v8, s55, v197
	v_cvt_pk_fp8_f32 v11, v11, v8
	v_mul_f32_e32 v9, v112, v9
	v_add_f32_e32 v10, 1.0, v13
	v_rcp_f32_e32 v10, v10
	v_mul_f32_e32 v9, v108, v9
	v_mul_f32_e32 v9, 0x3b800000, v9
	v_mul_f32_e32 v10, v113, v10
	v_mul_f32_e32 v8, v109, v10
	v_mul_f32_e32 v8, 0x3b800000, v8
	v_med3_f32 v9, v9, s55, v197
	v_med3_f32 v8, v8, s55, v197
	v_cvt_pk_fp8_f32 v11, v9, v8 op_sel:[0,0,1]
	v_mul_f32_e32 v8, 0xbd38aa3b, v102
	v_exp_f32_e32 v12, v8
	v_or_b32_e32 v7, 32, v6
	v_mad_i64_i32 v[8:9], s[24:25], v7, s58, v[4:5]
	v_add_f32_e32 v7, 1.0, v12
	v_mul_f32_e32 v12, 0x3d000000, v103
	v_mul_f32_e32 v13, 0xbd38aa3b, v103
	v_rcp_f32_e32 v7, v7
	v_exp_f32_e32 v13, v13
	v_mul_f32_e32 v16, 0x3d000000, v100
	v_mul_f32_e32 v7, v102, v7
	v_add_f32_e32 v10, 1.0, v13
	v_rcp_f32_e32 v10, v10
	v_mul_f32_e32 v7, v98, v7
	v_mul_f32_e32 v7, 0x3b800000, v7
	v_mul_f32_e32 v10, v103, v10
	v_mul_f32_e32 v14, 0xbd38aa3b, v104
	v_exp_f32_e32 v14, v14
	v_mul_f32_e32 v10, v99, v10
	v_mul_f32_e32 v10, 0x3b800000, v10
	v_med3_f32 v7, v7, s55, v197
	v_add_f32_e32 v13, 1.0, v14
	v_mul_f32_e32 v14, 0x3d000000, v105
	v_mul_f32_e32 v15, 0xbd38aa3b, v105
	v_rcp_f32_e32 v13, v13
	v_exp_f32_e32 v15, v15
	v_med3_f32 v10, v10, s55, v197
	v_cvt_pk_fp8_f32 v7, v7, v10
	v_mul_f32_e32 v12, v104, v13
	v_add_f32_e32 v13, 1.0, v15
	v_rcp_f32_e32 v13, v13
	v_mul_f32_e32 v12, v100, v12
	v_mul_f32_e32 v12, 0x3b800000, v12
	v_mul_f32_e32 v13, v105, v13
	v_mul_f32_e32 v10, v101, v13
	v_mul_f32_e32 v10, 0x3b800000, v10
	v_med3_f32 v12, v12, s55, v197
	v_med3_f32 v10, v10, s55, v197
	v_cvt_pk_fp8_f32 v7, v12, v10 op_sel:[0,0,1]
	v_mul_f32_e32 v12, 0xbd38aa3b, v94
	v_exp_f32_e32 v12, v12
	v_lshl_add_u64 v[8:9], v[8:9], 0, v[2:3]
	global_store_dword v[8:9], v11, off
	global_store_dword v[8:9], v7, off offset:64
	v_add_f32_e32 v8, 1.0, v12
	v_mul_f32_e32 v11, 0xbd38aa3b, v95
	v_rcp_f32_e32 v8, v8
	v_exp_f32_e32 v11, v11
	v_mul_f32_e32 v14, 0x3d000000, v92
	v_mul_f32_e32 v8, v94, v8
	v_add_f32_e32 v10, 1.0, v11
	v_rcp_f32_e32 v10, v10
	v_mul_f32_e32 v8, v90, v8
	v_mul_f32_e32 v8, 0x3b800000, v8
	v_med3_f32 v11, v8, s55, v197
	v_mul_f32_e32 v9, v95, v10
	v_mul_f32_e32 v12, 0xbd38aa3b, v96
	v_exp_f32_e32 v12, v12
	v_mul_f32_e32 v8, v91, v9
	v_mul_f32_e32 v8, 0x3b800000, v8
	v_add_f32_e32 v9, 1.0, v12
	v_mul_f32_e32 v13, 0xbd38aa3b, v97
	v_rcp_f32_e32 v9, v9
	v_exp_f32_e32 v13, v13
	v_med3_f32 v8, v8, s55, v197
	v_cvt_pk_fp8_f32 v11, v11, v8
	v_mul_f32_e32 v9, v96, v9
	v_add_f32_e32 v10, 1.0, v13
	v_rcp_f32_e32 v10, v10
	v_mul_f32_e32 v9, v92, v9
	v_mul_f32_e32 v9, 0x3b800000, v9
	v_mul_f32_e32 v10, v97, v10
	v_mul_f32_e32 v8, v93, v10
	v_mul_f32_e32 v8, 0x3b800000, v8
	v_med3_f32 v9, v9, s55, v197
	v_med3_f32 v8, v8, s55, v197
	v_cvt_pk_fp8_f32 v11, v9, v8 op_sel:[0,0,1]
	v_mul_f32_e32 v8, 0xbd38aa3b, v86
	v_exp_f32_e32 v12, v8
	v_or_b32_e32 v7, 48, v6
	v_mad_i64_i32 v[8:9], s[24:25], v7, s58, v[4:5]
	v_add_f32_e32 v7, 1.0, v12
	v_mul_f32_e32 v12, 0x3d000000, v87
	v_mul_f32_e32 v13, 0xbd38aa3b, v87
	v_rcp_f32_e32 v7, v7
	v_exp_f32_e32 v13, v13
	v_mul_f32_e32 v16, 0x3d000000, v84
	v_mul_f32_e32 v7, v86, v7
	v_add_f32_e32 v10, 1.0, v13
	v_rcp_f32_e32 v10, v10
	v_mul_f32_e32 v7, v82, v7
	v_mul_f32_e32 v7, 0x3b800000, v7
	v_mul_f32_e32 v10, v87, v10
	v_mul_f32_e32 v14, 0xbd38aa3b, v88
	v_exp_f32_e32 v14, v14
	v_mul_f32_e32 v10, v83, v10
	v_mul_f32_e32 v10, 0x3b800000, v10
	v_med3_f32 v7, v7, s55, v197
	v_add_f32_e32 v13, 1.0, v14
	v_mul_f32_e32 v14, 0x3d000000, v89
	v_mul_f32_e32 v15, 0xbd38aa3b, v89
	v_rcp_f32_e32 v13, v13
	v_exp_f32_e32 v15, v15
	v_med3_f32 v10, v10, s55, v197
	v_cvt_pk_fp8_f32 v7, v7, v10
	v_mul_f32_e32 v12, v88, v13
	v_add_f32_e32 v13, 1.0, v15
	v_rcp_f32_e32 v13, v13
	v_mul_f32_e32 v12, v84, v12
	v_mul_f32_e32 v12, 0x3b800000, v12
	v_mul_f32_e32 v13, v89, v13
	v_mul_f32_e32 v10, v85, v13
	v_mul_f32_e32 v10, 0x3b800000, v10
	v_med3_f32 v12, v12, s55, v197
	v_med3_f32 v10, v10, s55, v197
	v_cvt_pk_fp8_f32 v7, v12, v10 op_sel:[0,0,1]
	v_mul_f32_e32 v12, 0xbd38aa3b, v78
	v_exp_f32_e32 v12, v12
	v_lshl_add_u64 v[8:9], v[8:9], 0, v[2:3]
	global_store_dword v[8:9], v11, off
	global_store_dword v[8:9], v7, off offset:64
	v_add_f32_e32 v8, 1.0, v12
	v_mul_f32_e32 v11, 0xbd38aa3b, v79
	v_rcp_f32_e32 v8, v8
	v_exp_f32_e32 v11, v11
	v_mul_f32_e32 v14, 0x3d000000, v76
	v_mul_f32_e32 v8, v78, v8
	v_add_f32_e32 v10, 1.0, v11
	v_rcp_f32_e32 v10, v10
	v_mul_f32_e32 v8, v74, v8
	v_mul_f32_e32 v8, 0x3b800000, v8
	v_med3_f32 v11, v8, s55, v197
	v_mul_f32_e32 v9, v79, v10
	v_mul_f32_e32 v12, 0xbd38aa3b, v80
	v_exp_f32_e32 v12, v12
	v_mul_f32_e32 v8, v75, v9
	v_mul_f32_e32 v8, 0x3b800000, v8
	v_add_f32_e32 v9, 1.0, v12
	v_mul_f32_e32 v13, 0xbd38aa3b, v81
	v_rcp_f32_e32 v9, v9
	v_exp_f32_e32 v13, v13
	v_med3_f32 v8, v8, s55, v197
	v_cvt_pk_fp8_f32 v11, v11, v8
	v_mul_f32_e32 v9, v80, v9
	v_add_f32_e32 v10, 1.0, v13
	v_rcp_f32_e32 v10, v10
	v_mul_f32_e32 v9, v76, v9
	v_mul_f32_e32 v9, 0x3b800000, v9
	v_mul_f32_e32 v10, v81, v10
	v_mul_f32_e32 v8, v77, v10
	v_mul_f32_e32 v8, 0x3b800000, v8
	v_med3_f32 v9, v9, s55, v197
	v_med3_f32 v8, v8, s55, v197
	v_cvt_pk_fp8_f32 v11, v9, v8 op_sel:[0,0,1]
	v_mul_f32_e32 v8, 0xbd38aa3b, v70
	v_exp_f32_e32 v12, v8
	v_add_u32_e32 v7, 0x80, v6
	v_mad_i64_i32 v[8:9], s[24:25], v7, s58, v[4:5]
	v_add_f32_e32 v7, 1.0, v12
	v_mul_f32_e32 v12, 0x3d000000, v71
	v_mul_f32_e32 v13, 0xbd38aa3b, v71
	v_rcp_f32_e32 v7, v7
	v_exp_f32_e32 v13, v13
	v_mul_f32_e32 v16, 0x3d000000, v68
	v_mul_f32_e32 v7, v70, v7
	v_add_f32_e32 v10, 1.0, v13
	v_rcp_f32_e32 v10, v10
	v_mul_f32_e32 v7, v66, v7
	v_mul_f32_e32 v7, 0x3b800000, v7
	v_mul_f32_e32 v10, v71, v10
	v_mul_f32_e32 v14, 0xbd38aa3b, v72
	v_exp_f32_e32 v14, v14
	v_mul_f32_e32 v10, v67, v10
	v_mul_f32_e32 v10, 0x3b800000, v10
	v_med3_f32 v7, v7, s55, v197
	v_add_f32_e32 v13, 1.0, v14
	v_mul_f32_e32 v14, 0x3d000000, v73
	v_mul_f32_e32 v15, 0xbd38aa3b, v73
	v_rcp_f32_e32 v13, v13
	v_exp_f32_e32 v15, v15
	v_med3_f32 v10, v10, s55, v197
	v_cvt_pk_fp8_f32 v7, v7, v10
	v_mul_f32_e32 v12, v72, v13
	v_add_f32_e32 v13, 1.0, v15
	v_rcp_f32_e32 v13, v13
	v_mul_f32_e32 v12, v68, v12
	v_mul_f32_e32 v12, 0x3b800000, v12
	v_mul_f32_e32 v13, v73, v13
	v_mul_f32_e32 v10, v69, v13
	v_mul_f32_e32 v10, 0x3b800000, v10
	v_med3_f32 v12, v12, s55, v197
	v_med3_f32 v10, v10, s55, v197
	v_cvt_pk_fp8_f32 v7, v12, v10 op_sel:[0,0,1]
	v_mul_f32_e32 v12, 0xbd38aa3b, v62
	v_exp_f32_e32 v12, v12
	v_lshl_add_u64 v[8:9], v[8:9], 0, v[2:3]
	global_store_dword v[8:9], v11, off
	global_store_dword v[8:9], v7, off offset:64
	v_add_f32_e32 v8, 1.0, v12
	v_mul_f32_e32 v11, 0xbd38aa3b, v63
	v_rcp_f32_e32 v8, v8
	v_exp_f32_e32 v11, v11
	v_mul_f32_e32 v14, 0x3d000000, v60
	v_mul_f32_e32 v8, v62, v8
	v_add_f32_e32 v10, 1.0, v11
	v_rcp_f32_e32 v10, v10
	v_mul_f32_e32 v8, v58, v8
	v_mul_f32_e32 v8, 0x3b800000, v8
	v_med3_f32 v11, v8, s55, v197
	v_mul_f32_e32 v9, v63, v10
	v_mul_f32_e32 v12, 0xbd38aa3b, v64
	v_exp_f32_e32 v12, v12
	v_mul_f32_e32 v8, v59, v9
	v_mul_f32_e32 v8, 0x3b800000, v8
	v_add_f32_e32 v9, 1.0, v12
	v_mul_f32_e32 v13, 0xbd38aa3b, v65
	v_rcp_f32_e32 v9, v9
	v_exp_f32_e32 v13, v13
	v_med3_f32 v8, v8, s55, v197
	v_cvt_pk_fp8_f32 v11, v11, v8
	v_mul_f32_e32 v9, v64, v9
	v_add_f32_e32 v10, 1.0, v13
	v_rcp_f32_e32 v10, v10
	v_mul_f32_e32 v9, v60, v9
	v_mul_f32_e32 v9, 0x3b800000, v9
	v_mul_f32_e32 v10, v65, v10
	v_mul_f32_e32 v8, v61, v10
	v_mul_f32_e32 v8, 0x3b800000, v8
	v_med3_f32 v9, v9, s55, v197
	v_med3_f32 v8, v8, s55, v197
	v_cvt_pk_fp8_f32 v11, v9, v8 op_sel:[0,0,1]
	v_mul_f32_e32 v8, 0xbd38aa3b, v54
	v_exp_f32_e32 v12, v8
	v_add_u32_e32 v7, 0x90, v6
	v_mad_i64_i32 v[8:9], s[24:25], v7, s58, v[4:5]
	v_add_f32_e32 v7, 1.0, v12
	v_mul_f32_e32 v12, 0x3d000000, v55
	v_mul_f32_e32 v13, 0xbd38aa3b, v55
	v_rcp_f32_e32 v7, v7
	v_exp_f32_e32 v13, v13
	v_mul_f32_e32 v16, 0x3d000000, v52
	v_mul_f32_e32 v7, v54, v7
	v_add_f32_e32 v10, 1.0, v13
	v_rcp_f32_e32 v10, v10
	v_mul_f32_e32 v7, v50, v7
	v_mul_f32_e32 v7, 0x3b800000, v7
	v_mul_f32_e32 v10, v55, v10
	v_mul_f32_e32 v14, 0xbd38aa3b, v56
	v_exp_f32_e32 v14, v14
	v_mul_f32_e32 v10, v51, v10
	v_mul_f32_e32 v10, 0x3b800000, v10
	v_med3_f32 v7, v7, s55, v197
	v_add_f32_e32 v13, 1.0, v14
	v_mul_f32_e32 v14, 0x3d000000, v57
	v_mul_f32_e32 v15, 0xbd38aa3b, v57
	v_rcp_f32_e32 v13, v13
	v_exp_f32_e32 v15, v15
	v_med3_f32 v10, v10, s55, v197
	v_cvt_pk_fp8_f32 v7, v7, v10
	v_mul_f32_e32 v12, v56, v13
	v_add_f32_e32 v13, 1.0, v15
	v_rcp_f32_e32 v13, v13
	v_mul_f32_e32 v12, v52, v12
	v_mul_f32_e32 v12, 0x3b800000, v12
	v_mul_f32_e32 v13, v57, v13
	v_mul_f32_e32 v10, v53, v13
	v_mul_f32_e32 v10, 0x3b800000, v10
	v_med3_f32 v12, v12, s55, v197
	v_med3_f32 v10, v10, s55, v197
	v_cvt_pk_fp8_f32 v7, v12, v10 op_sel:[0,0,1]
	v_mul_f32_e32 v12, 0xbd38aa3b, v46
	v_exp_f32_e32 v12, v12
	v_lshl_add_u64 v[8:9], v[8:9], 0, v[2:3]
	global_store_dword v[8:9], v11, off
	global_store_dword v[8:9], v7, off offset:64
	v_add_f32_e32 v8, 1.0, v12
	v_mul_f32_e32 v11, 0xbd38aa3b, v47
	v_rcp_f32_e32 v8, v8
	v_exp_f32_e32 v11, v11
	v_mul_f32_e32 v14, 0x3d000000, v44
	v_mul_f32_e32 v8, v46, v8
	v_add_f32_e32 v10, 1.0, v11
	v_rcp_f32_e32 v10, v10
	v_mul_f32_e32 v8, v42, v8
	v_mul_f32_e32 v8, 0x3b800000, v8
	v_med3_f32 v11, v8, s55, v197
	v_mul_f32_e32 v9, v47, v10
	v_mul_f32_e32 v12, 0xbd38aa3b, v48
	v_exp_f32_e32 v12, v12
	v_mul_f32_e32 v8, v43, v9
	v_mul_f32_e32 v8, 0x3b800000, v8
	v_add_f32_e32 v9, 1.0, v12
	v_mul_f32_e32 v13, 0xbd38aa3b, v49
	v_rcp_f32_e32 v9, v9
	v_exp_f32_e32 v13, v13
	v_med3_f32 v8, v8, s55, v197
	v_cvt_pk_fp8_f32 v11, v11, v8
	v_mul_f32_e32 v9, v48, v9
	v_add_f32_e32 v10, 1.0, v13
	v_rcp_f32_e32 v10, v10
	v_mul_f32_e32 v9, v44, v9
	v_mul_f32_e32 v9, 0x3b800000, v9
	v_mul_f32_e32 v10, v49, v10
	v_mul_f32_e32 v8, v45, v10
	v_mul_f32_e32 v8, 0x3b800000, v8
	v_med3_f32 v9, v9, s55, v197
	v_med3_f32 v8, v8, s55, v197
	v_cvt_pk_fp8_f32 v11, v9, v8 op_sel:[0,0,1]
	v_mul_f32_e32 v8, 0xbd38aa3b, v38
	v_exp_f32_e32 v12, v8
	v_add_u32_e32 v7, 0xa0, v6
	v_mad_i64_i32 v[8:9], s[24:25], v7, s58, v[4:5]
	v_add_f32_e32 v7, 1.0, v12
	v_mul_f32_e32 v12, 0x3d000000, v39
	v_mul_f32_e32 v13, 0xbd38aa3b, v39
	v_rcp_f32_e32 v7, v7
	v_exp_f32_e32 v13, v13
	v_mul_f32_e32 v7, v38, v7
	v_add_f32_e32 v10, 1.0, v13
	v_rcp_f32_e32 v10, v10
	v_mul_f32_e32 v7, v34, v7
	v_mul_f32_e32 v7, 0x3b800000, v7
	v_mul_f32_e32 v10, v39, v10
	v_mul_f32_e32 v14, 0xbd38aa3b, v40
	v_exp_f32_e32 v14, v14
	v_mul_f32_e32 v10, v35, v10
	v_mul_f32_e32 v10, 0x3b800000, v10
	v_med3_f32 v7, v7, s55, v197
	v_add_f32_e32 v13, 1.0, v14
	v_mul_f32_e32 v14, 0x3d000000, v41
	v_mul_f32_e32 v15, 0xbd38aa3b, v41
	v_rcp_f32_e32 v13, v13
	v_exp_f32_e32 v15, v15
	v_med3_f32 v10, v10, s55, v197
	v_cvt_pk_fp8_f32 v7, v7, v10
	v_mul_f32_e32 v12, v40, v13
	v_add_f32_e32 v13, 1.0, v15
	v_rcp_f32_e32 v13, v13
	v_mul_f32_e32 v12, v36, v12
	v_mul_f32_e32 v12, 0x3b800000, v12
	v_mul_f32_e32 v13, v41, v13
	v_mul_f32_e32 v10, v37, v13
	v_mul_f32_e32 v10, 0x3b800000, v10
	v_med3_f32 v12, v12, s55, v197
	v_med3_f32 v10, v10, s55, v197
	v_cvt_pk_fp8_f32 v7, v12, v10 op_sel:[0,0,1]
	v_lshl_add_u64 v[8:9], v[8:9], 0, v[2:3]
	v_mul_f32_e32 v10, 0x3d000000, v30
	global_store_dword v[8:9], v11, off
	global_store_dword v[8:9], v7, off offset:64
	v_mul_f32_e32 v12, 0xbd38aa3b, v30
	v_mul_f32_e32 v9, 0xbd38aa3b, v31
	v_exp_f32_e32 v12, v12
	v_exp_f32_e32 v9, v9
	v_add_f32_e32 v7, 1.0, v12
	v_add_f32_e32 v9, 1.0, v9
	v_rcp_f32_e32 v7, v7
	v_rcp_f32_e32 v9, v9
	v_add_u32_e32 v6, 0xb0, v6
	v_mul_f32_e32 v7, v30, v7
	v_mul_f32_e32 v8, v31, v9
	v_mul_f32_e32 v7, v26, v7
	v_mul_f32_e32 v11, 0xbd38aa3b, v32
	v_exp_f32_e32 v11, v11
	v_mul_f32_e32 v8, v27, v8
	v_mul_f32_e32 v7, 0x3b800000, v7
	v_add_f32_e32 v10, 1.0, v11
	v_mul_f32_e32 v12, 0xbd38aa3b, v33
	v_rcp_f32_e32 v10, v10
	v_exp_f32_e32 v12, v12
	v_mul_f32_e32 v8, 0x3b800000, v8
	v_med3_f32 v7, v7, s55, v197
	v_mul_f32_e32 v9, v32, v10
	v_add_f32_e32 v10, 1.0, v12
	v_rcp_f32_e32 v10, v10
	v_med3_f32 v8, v8, s55, v197
	v_cvt_pk_fp8_f32 v7, v7, v8
	v_mul_f32_e32 v12, 0x3d000000, v29
	v_mul_f32_e32 v10, v33, v10
	v_mul_f32_e32 v11, 0xbd38aa3b, v22
	v_mul_f32_e32 v9, v28, v9
	v_mul_f32_e32 v10, v29, v10
	v_exp_f32_e32 v11, v11
	v_mul_f32_e32 v9, 0x3b800000, v9
	v_mul_f32_e32 v10, 0x3b800000, v10
	v_med3_f32 v9, v9, s55, v197
	v_med3_f32 v10, v10, s55, v197
	v_cvt_pk_fp8_f32 v7, v9, v10 op_sel:[0,0,1]
	v_mul_f32_e32 v10, 0x3d000000, v23
	v_add_f32_e32 v9, 1.0, v11
	v_mul_f32_e32 v11, 0xbd38aa3b, v23
	v_rcp_f32_e32 v9, v9
	v_exp_f32_e32 v11, v11
	v_mad_i64_i32 v[4:5], s[24:25], v6, s58, v[4:5]
	v_mul_f32_e32 v8, v22, v9
	v_add_f32_e32 v9, 1.0, v11
	v_rcp_f32_e32 v9, v9
	v_mul_f32_e32 v8, v18, v8
	v_mul_f32_e32 v8, 0x3b800000, v8
	v_mul_f32_e32 v9, v23, v9
	v_mul_f32_e32 v12, 0xbd38aa3b, v24
	v_exp_f32_e32 v12, v12
	v_mul_f32_e32 v9, v19, v9
	v_mul_f32_e32 v9, 0x3b800000, v9
	v_med3_f32 v8, v8, s55, v197
	v_add_f32_e32 v11, 1.0, v12
	v_mul_f32_e32 v13, 0xbd38aa3b, v25
	v_rcp_f32_e32 v11, v11
	v_exp_f32_e32 v13, v13
	v_med3_f32 v9, v9, s55, v197
	v_cvt_pk_fp8_f32 v8, v8, v9
	v_mul_f32_e32 v10, v24, v11
	v_add_f32_e32 v11, 1.0, v13
	v_rcp_f32_e32 v11, v11
	v_mul_f32_e32 v10, v20, v10
	v_mul_f32_e32 v10, 0x3b800000, v10
	v_mul_f32_e32 v11, v25, v11
	v_mul_f32_e32 v9, v21, v11
	v_mul_f32_e32 v9, 0x3b800000, v9
	v_med3_f32 v10, v10, s55, v197
	v_med3_f32 v9, v9, s55, v197
	v_cvt_pk_fp8_f32 v8, v10, v9 op_sel:[0,0,1]
	v_lshl_add_u64 v[2:3], v[4:5], 0, v[2:3]
	v_mov_b32_e32 v200, v161
	v_mov_b32_e32 v158, v163
	v_mov_b32_e32 v160, v198
	v_mov_b32_e32 v162, v199
	s_mov_b32 s22, s18
	s_mov_b32 s60, s59
	s_mov_b64 s[24:25], s[20:21]
	global_store_dword v[2:3], v7, off
	global_store_dword v[2:3], v8, off offset:64
	s_cbranch_vccz .LBB0_5613
	s_waitcnt vmcnt(0)
	s_cmpk_gt_u32 s31, 0xff
	s_cbranch_scc1 .LBB0_5620
	s_barrier
